# v095 + P0 mix rewritten (contiguous token blocks, x row reuse, deep prefetch, nt loads)
# speedup vs baseline: 1.0083x; 1.0083x over previous
.LBB0_64:
	s_cmp_eq_u32 s24, 0x100
	s_cbranch_scc0 .Lmix0_orig
	s_load_dwordx2 s[16:17], s[0:1], 0x8
	s_load_dwordx2 s[18:19], s[0:1], 0x0
	s_load_dwordx2 s[20:21], s[0:1], 0xe0
	v_lshlrev_b32_e32 v1, 4, v190
	v_lshlrev_b32_e32 v2, 3, v190
	s_lshl_b32 s3, s2, 19
	s_lshl_b32 s22, s2, 18
	s_waitcnt lgkmcnt(0)
	s_add_u32 s12, s16, 0x0
	s_addc_u32 s13, s17, 0
	global_load_dwordx4 v[4:7], v1, s[12:13]
	s_add_u32 s12, s16, 0x4000
	s_addc_u32 s13, s17, 0
	global_load_dwordx4 v[8:11], v1, s[12:13]
	s_add_u32 s12, s16, 0x6000
	s_addc_u32 s13, s17, 0
	global_load_dwordx4 v[12:15], v1, s[12:13]
	s_add_u32 s4, s18, s3
	s_addc_u32 s5, s19, 0
	s_add_u32 s6, s20, 0x8100000
	s_addc_u32 s7, s21, 0
	s_add_u32 s6, s6, s22
	s_addc_u32 s7, s7, 0
	s_add_u32 s8, s6, 0x4000000
	s_addc_u32 s9, s7, 0
	s_add_u32 s10, s6, 0x8000000
	s_addc_u32 s11, s7, 0
	v_mov_b32_e32 v16, 0
	v_mov_b32_e32 v17, 0
	v_mov_b32_e32 v18, 0
	v_mov_b32_e32 v19, 0
	s_and_b32 s3, s2, 63
	s_cmp_eq_u32 s3, 0
	s_cbranch_scc1 .Lmix0_noprev
	s_sub_u32 s22, s4, 0x2000
	s_subb_u32 s23, s5, 0
	global_load_dwordx4 v[16:19], v1, s[22:23] nt
.Lmix0_noprev:
	global_load_dwordx4 v[20:23], v1, s[4:5] nt
	s_add_u32 s4, s4, 0x2000
	s_addc_u32 s5, s5, 0
	global_load_dwordx4 v[24:27], v1, s[4:5] nt
	s_add_u32 s4, s4, 0x2000
	s_addc_u32 s5, s5, 0
	global_load_dwordx4 v[28:31], v1, s[4:5] nt
	s_add_u32 s4, s4, 0x2000
	s_addc_u32 s5, s5, 0
	global_load_dwordx4 v[32:35], v1, s[4:5] nt
	s_add_u32 s4, s4, 0x2000
	s_addc_u32 s5, s5, 0
	global_load_dwordx4 v[36:39], v1, s[4:5] nt
	s_add_u32 s4, s4, 0x2000
	s_addc_u32 s5, s5, 0
	global_load_dwordx4 v[40:43], v1, s[4:5] nt
	s_add_u32 s4, s4, 0x2000
	s_addc_u32 s5, s5, 0
	global_load_dwordx4 v[44:47], v1, s[4:5] nt
	s_add_u32 s4, s4, 0x2000
	s_addc_u32 s5, s5, 0
	global_load_dwordx4 v[48:51], v1, s[4:5] nt
	s_add_u32 s4, s4, 0x2000
	s_addc_u32 s5, s5, 0
	global_load_dwordx4 v[52:55], v1, s[4:5] nt
	s_add_u32 s4, s4, 0x2000
	s_addc_u32 s5, s5, 0
	global_load_dwordx4 v[56:59], v1, s[4:5] nt
	s_add_u32 s4, s4, 0x2000
	s_addc_u32 s5, s5, 0
	global_load_dwordx4 v[60:63], v1, s[4:5] nt
	s_add_u32 s4, s4, 0x2000
	s_addc_u32 s5, s5, 0
	global_load_dwordx4 v[64:67], v1, s[4:5] nt
	s_add_u32 s4, s4, 0x2000
	s_addc_u32 s5, s5, 0
	global_load_dwordx4 v[68:71], v1, s[4:5] nt
	s_add_u32 s4, s4, 0x2000
	s_addc_u32 s5, s5, 0
	global_load_dwordx4 v[72:75], v1, s[4:5] nt
	s_add_u32 s4, s4, 0x2000
	s_addc_u32 s5, s5, 0
	global_load_dwordx4 v[76:79], v1, s[4:5] nt
	s_add_u32 s4, s4, 0x2000
	s_addc_u32 s5, s5, 0
	global_load_dwordx4 v[80:83], v1, s[4:5] nt
	s_add_u32 s4, s4, 0x2000
	s_addc_u32 s5, s5, 0
	s_waitcnt vmcnt(15)
	v_sub_f32_e32 v84, v16, v20
	v_sub_f32_e32 v85, v17, v21
	v_sub_f32_e32 v86, v18, v22
	v_sub_f32_e32 v87, v19, v23
	v_pk_fma_f32 v[88:89], v[84:85], v[4:5], v[20:21]
	v_pk_fma_f32 v[90:91], v[86:87], v[6:7], v[22:23]
	v_pk_fma_f32 v[92:93], v[84:85], v[8:9], v[20:21]
	v_pk_fma_f32 v[94:95], v[86:87], v[10:11], v[22:23]
	v_pk_fma_f32 v[96:97], v[84:85], v[12:13], v[20:21]
	v_pk_fma_f32 v[98:99], v[86:87], v[14:15], v[22:23]
	v_cvt_pk_bf16_f32 v100, v88, v89
	v_cvt_pk_bf16_f32 v101, v90, v91
	v_cvt_pk_bf16_f32 v102, v92, v93
	v_cvt_pk_bf16_f32 v103, v94, v95
	v_cvt_pk_bf16_f32 v104, v96, v97
	v_cvt_pk_bf16_f32 v105, v98, v99
	global_store_dwordx2 v2, v[100:101], s[6:7]
	global_store_dwordx2 v2, v[102:103], s[8:9]
	global_store_dwordx2 v2, v[104:105], s[10:11]
	s_add_u32 s6, s6, 0x1000
	s_addc_u32 s7, s7, 0
	s_add_u32 s8, s8, 0x1000
	s_addc_u32 s9, s9, 0
	s_add_u32 s10, s10, 0x1000
	s_addc_u32 s11, s11, 0
	s_waitcnt vmcnt(17)
	v_sub_f32_e32 v84, v20, v24
	v_sub_f32_e32 v85, v21, v25
	v_sub_f32_e32 v86, v22, v26
	v_sub_f32_e32 v87, v23, v27
	v_pk_fma_f32 v[88:89], v[84:85], v[4:5], v[24:25]
	v_pk_fma_f32 v[90:91], v[86:87], v[6:7], v[26:27]
	v_pk_fma_f32 v[92:93], v[84:85], v[8:9], v[24:25]
	v_pk_fma_f32 v[94:95], v[86:87], v[10:11], v[26:27]
	v_pk_fma_f32 v[96:97], v[84:85], v[12:13], v[24:25]
	v_pk_fma_f32 v[98:99], v[86:87], v[14:15], v[26:27]
	v_cvt_pk_bf16_f32 v106, v88, v89
	v_cvt_pk_bf16_f32 v107, v90, v91
	v_cvt_pk_bf16_f32 v108, v92, v93
	v_cvt_pk_bf16_f32 v109, v94, v95
	v_cvt_pk_bf16_f32 v110, v96, v97
	v_cvt_pk_bf16_f32 v111, v98, v99
	global_store_dwordx2 v2, v[106:107], s[6:7]
	global_store_dwordx2 v2, v[108:109], s[8:9]
	global_store_dwordx2 v2, v[110:111], s[10:11]
	s_add_u32 s6, s6, 0x1000
	s_addc_u32 s7, s7, 0
	s_add_u32 s8, s8, 0x1000
	s_addc_u32 s9, s9, 0
	s_add_u32 s10, s10, 0x1000
	s_addc_u32 s11, s11, 0
	s_waitcnt vmcnt(19)
	v_sub_f32_e32 v84, v24, v28
	v_sub_f32_e32 v85, v25, v29
	v_sub_f32_e32 v86, v26, v30
	v_sub_f32_e32 v87, v27, v31
	v_pk_fma_f32 v[88:89], v[84:85], v[4:5], v[28:29]
	v_pk_fma_f32 v[90:91], v[86:87], v[6:7], v[30:31]
	v_pk_fma_f32 v[92:93], v[84:85], v[8:9], v[28:29]
	v_pk_fma_f32 v[94:95], v[86:87], v[10:11], v[30:31]
	v_pk_fma_f32 v[96:97], v[84:85], v[12:13], v[28:29]
	v_pk_fma_f32 v[98:99], v[86:87], v[14:15], v[30:31]
	v_cvt_pk_bf16_f32 v100, v88, v89
	v_cvt_pk_bf16_f32 v101, v90, v91
	v_cvt_pk_bf16_f32 v102, v92, v93
	v_cvt_pk_bf16_f32 v103, v94, v95
	v_cvt_pk_bf16_f32 v104, v96, v97
	v_cvt_pk_bf16_f32 v105, v98, v99
	global_store_dwordx2 v2, v[100:101], s[6:7]
	global_store_dwordx2 v2, v[102:103], s[8:9]
	global_store_dwordx2 v2, v[104:105], s[10:11]
	s_add_u32 s6, s6, 0x1000
	s_addc_u32 s7, s7, 0
	s_add_u32 s8, s8, 0x1000
	s_addc_u32 s9, s9, 0
	s_add_u32 s10, s10, 0x1000
	s_addc_u32 s11, s11, 0
	s_waitcnt vmcnt(21)
	v_sub_f32_e32 v84, v28, v32
	v_sub_f32_e32 v85, v29, v33
	v_sub_f32_e32 v86, v30, v34
	v_sub_f32_e32 v87, v31, v35
	v_pk_fma_f32 v[88:89], v[84:85], v[4:5], v[32:33]
	v_pk_fma_f32 v[90:91], v[86:87], v[6:7], v[34:35]
	v_pk_fma_f32 v[92:93], v[84:85], v[8:9], v[32:33]
	v_pk_fma_f32 v[94:95], v[86:87], v[10:11], v[34:35]
	v_pk_fma_f32 v[96:97], v[84:85], v[12:13], v[32:33]
	v_pk_fma_f32 v[98:99], v[86:87], v[14:15], v[34:35]
	v_cvt_pk_bf16_f32 v106, v88, v89
	v_cvt_pk_bf16_f32 v107, v90, v91
	v_cvt_pk_bf16_f32 v108, v92, v93
	v_cvt_pk_bf16_f32 v109, v94, v95
	v_cvt_pk_bf16_f32 v110, v96, v97
	v_cvt_pk_bf16_f32 v111, v98, v99
	global_store_dwordx2 v2, v[106:107], s[6:7]
	global_store_dwordx2 v2, v[108:109], s[8:9]
	global_store_dwordx2 v2, v[110:111], s[10:11]
	s_add_u32 s6, s6, 0x1000
	s_addc_u32 s7, s7, 0
	s_add_u32 s8, s8, 0x1000
	s_addc_u32 s9, s9, 0
	s_add_u32 s10, s10, 0x1000
	s_addc_u32 s11, s11, 0
	s_waitcnt vmcnt(23)
	v_sub_f32_e32 v84, v32, v36
	v_sub_f32_e32 v85, v33, v37
	v_sub_f32_e32 v86, v34, v38
	v_sub_f32_e32 v87, v35, v39
	v_pk_fma_f32 v[88:89], v[84:85], v[4:5], v[36:37]
	v_pk_fma_f32 v[90:91], v[86:87], v[6:7], v[38:39]
	v_pk_fma_f32 v[92:93], v[84:85], v[8:9], v[36:37]
	v_pk_fma_f32 v[94:95], v[86:87], v[10:11], v[38:39]
	v_pk_fma_f32 v[96:97], v[84:85], v[12:13], v[36:37]
	v_pk_fma_f32 v[98:99], v[86:87], v[14:15], v[38:39]
	v_cvt_pk_bf16_f32 v100, v88, v89
	v_cvt_pk_bf16_f32 v101, v90, v91
	v_cvt_pk_bf16_f32 v102, v92, v93
	v_cvt_pk_bf16_f32 v103, v94, v95
	v_cvt_pk_bf16_f32 v104, v96, v97
	v_cvt_pk_bf16_f32 v105, v98, v99
	global_store_dwordx2 v2, v[100:101], s[6:7]
	global_store_dwordx2 v2, v[102:103], s[8:9]
	global_store_dwordx2 v2, v[104:105], s[10:11]
	s_add_u32 s6, s6, 0x1000
	s_addc_u32 s7, s7, 0
	s_add_u32 s8, s8, 0x1000
	s_addc_u32 s9, s9, 0
	s_add_u32 s10, s10, 0x1000
	s_addc_u32 s11, s11, 0
	s_waitcnt vmcnt(25)
	v_sub_f32_e32 v84, v36, v40
	v_sub_f32_e32 v85, v37, v41
	v_sub_f32_e32 v86, v38, v42
	v_sub_f32_e32 v87, v39, v43
	v_pk_fma_f32 v[88:89], v[84:85], v[4:5], v[40:41]
	v_pk_fma_f32 v[90:91], v[86:87], v[6:7], v[42:43]
	v_pk_fma_f32 v[92:93], v[84:85], v[8:9], v[40:41]
	v_pk_fma_f32 v[94:95], v[86:87], v[10:11], v[42:43]
	v_pk_fma_f32 v[96:97], v[84:85], v[12:13], v[40:41]
	v_pk_fma_f32 v[98:99], v[86:87], v[14:15], v[42:43]
	v_cvt_pk_bf16_f32 v106, v88, v89
	v_cvt_pk_bf16_f32 v107, v90, v91
	v_cvt_pk_bf16_f32 v108, v92, v93
	v_cvt_pk_bf16_f32 v109, v94, v95
	v_cvt_pk_bf16_f32 v110, v96, v97
	v_cvt_pk_bf16_f32 v111, v98, v99
	global_store_dwordx2 v2, v[106:107], s[6:7]
	global_store_dwordx2 v2, v[108:109], s[8:9]
	global_store_dwordx2 v2, v[110:111], s[10:11]
	s_add_u32 s6, s6, 0x1000
	s_addc_u32 s7, s7, 0
	s_add_u32 s8, s8, 0x1000
	s_addc_u32 s9, s9, 0
	s_add_u32 s10, s10, 0x1000
	s_addc_u32 s11, s11, 0
	s_waitcnt vmcnt(27)
	v_sub_f32_e32 v84, v40, v44
	v_sub_f32_e32 v85, v41, v45
	v_sub_f32_e32 v86, v42, v46
	v_sub_f32_e32 v87, v43, v47
	v_pk_fma_f32 v[88:89], v[84:85], v[4:5], v[44:45]
	v_pk_fma_f32 v[90:91], v[86:87], v[6:7], v[46:47]
	v_pk_fma_f32 v[92:93], v[84:85], v[8:9], v[44:45]
	v_pk_fma_f32 v[94:95], v[86:87], v[10:11], v[46:47]
	v_pk_fma_f32 v[96:97], v[84:85], v[12:13], v[44:45]
	v_pk_fma_f32 v[98:99], v[86:87], v[14:15], v[46:47]
	v_cvt_pk_bf16_f32 v100, v88, v89
	v_cvt_pk_bf16_f32 v101, v90, v91
	v_cvt_pk_bf16_f32 v102, v92, v93
	v_cvt_pk_bf16_f32 v103, v94, v95
	v_cvt_pk_bf16_f32 v104, v96, v97
	v_cvt_pk_bf16_f32 v105, v98, v99
	global_store_dwordx2 v2, v[100:101], s[6:7]
	global_store_dwordx2 v2, v[102:103], s[8:9]
	global_store_dwordx2 v2, v[104:105], s[10:11]
	s_add_u32 s6, s6, 0x1000
	s_addc_u32 s7, s7, 0
	s_add_u32 s8, s8, 0x1000
	s_addc_u32 s9, s9, 0
	s_add_u32 s10, s10, 0x1000
	s_addc_u32 s11, s11, 0
	s_waitcnt vmcnt(29)
	v_sub_f32_e32 v84, v44, v48
	v_sub_f32_e32 v85, v45, v49
	v_sub_f32_e32 v86, v46, v50
	v_sub_f32_e32 v87, v47, v51
	v_pk_fma_f32 v[88:89], v[84:85], v[4:5], v[48:49]
	v_pk_fma_f32 v[90:91], v[86:87], v[6:7], v[50:51]
	v_pk_fma_f32 v[92:93], v[84:85], v[8:9], v[48:49]
	v_pk_fma_f32 v[94:95], v[86:87], v[10:11], v[50:51]
	v_pk_fma_f32 v[96:97], v[84:85], v[12:13], v[48:49]
	v_pk_fma_f32 v[98:99], v[86:87], v[14:15], v[50:51]
	v_cvt_pk_bf16_f32 v106, v88, v89
	v_cvt_pk_bf16_f32 v107, v90, v91
	v_cvt_pk_bf16_f32 v108, v92, v93
	v_cvt_pk_bf16_f32 v109, v94, v95
	v_cvt_pk_bf16_f32 v110, v96, v97
	v_cvt_pk_bf16_f32 v111, v98, v99
	global_store_dwordx2 v2, v[106:107], s[6:7]
	global_store_dwordx2 v2, v[108:109], s[8:9]
	global_store_dwordx2 v2, v[110:111], s[10:11]
	s_add_u32 s6, s6, 0x1000
	s_addc_u32 s7, s7, 0
	s_add_u32 s8, s8, 0x1000
	s_addc_u32 s9, s9, 0
	s_add_u32 s10, s10, 0x1000
	s_addc_u32 s11, s11, 0
	v_mov_b32_e32 v16, v48
	v_mov_b32_e32 v17, v49
	v_mov_b32_e32 v18, v50
	v_mov_b32_e32 v19, v51
	global_load_dwordx4 v[20:23], v1, s[4:5] nt
	s_add_u32 s4, s4, 0x2000
	s_addc_u32 s5, s5, 0
	global_load_dwordx4 v[24:27], v1, s[4:5] nt
	s_add_u32 s4, s4, 0x2000
	s_addc_u32 s5, s5, 0
	global_load_dwordx4 v[28:31], v1, s[4:5] nt
	s_add_u32 s4, s4, 0x2000
	s_addc_u32 s5, s5, 0
	global_load_dwordx4 v[32:35], v1, s[4:5] nt
	s_add_u32 s4, s4, 0x2000
	s_addc_u32 s5, s5, 0
	global_load_dwordx4 v[36:39], v1, s[4:5] nt
	s_add_u32 s4, s4, 0x2000
	s_addc_u32 s5, s5, 0
	global_load_dwordx4 v[40:43], v1, s[4:5] nt
	s_add_u32 s4, s4, 0x2000
	s_addc_u32 s5, s5, 0
	global_load_dwordx4 v[44:47], v1, s[4:5] nt
	s_add_u32 s4, s4, 0x2000
	s_addc_u32 s5, s5, 0
	global_load_dwordx4 v[48:51], v1, s[4:5] nt
	s_add_u32 s4, s4, 0x2000
	s_addc_u32 s5, s5, 0
	s_waitcnt vmcnt(39)
	v_sub_f32_e32 v84, v16, v52
	v_sub_f32_e32 v85, v17, v53
	v_sub_f32_e32 v86, v18, v54
	v_sub_f32_e32 v87, v19, v55
	v_pk_fma_f32 v[88:89], v[84:85], v[4:5], v[52:53]
	v_pk_fma_f32 v[90:91], v[86:87], v[6:7], v[54:55]
	v_pk_fma_f32 v[92:93], v[84:85], v[8:9], v[52:53]
	v_pk_fma_f32 v[94:95], v[86:87], v[10:11], v[54:55]
	v_pk_fma_f32 v[96:97], v[84:85], v[12:13], v[52:53]
	v_pk_fma_f32 v[98:99], v[86:87], v[14:15], v[54:55]
	v_cvt_pk_bf16_f32 v100, v88, v89
	v_cvt_pk_bf16_f32 v101, v90, v91
	v_cvt_pk_bf16_f32 v102, v92, v93
	v_cvt_pk_bf16_f32 v103, v94, v95
	v_cvt_pk_bf16_f32 v104, v96, v97
	v_cvt_pk_bf16_f32 v105, v98, v99
	global_store_dwordx2 v2, v[100:101], s[6:7]
	global_store_dwordx2 v2, v[102:103], s[8:9]
	global_store_dwordx2 v2, v[104:105], s[10:11]
	s_add_u32 s6, s6, 0x1000
	s_addc_u32 s7, s7, 0
	s_add_u32 s8, s8, 0x1000
	s_addc_u32 s9, s9, 0
	s_add_u32 s10, s10, 0x1000
	s_addc_u32 s11, s11, 0
	s_waitcnt vmcnt(41)
	v_sub_f32_e32 v84, v52, v56
	v_sub_f32_e32 v85, v53, v57
	v_sub_f32_e32 v86, v54, v58
	v_sub_f32_e32 v87, v55, v59
	v_pk_fma_f32 v[88:89], v[84:85], v[4:5], v[56:57]
	v_pk_fma_f32 v[90:91], v[86:87], v[6:7], v[58:59]
	v_pk_fma_f32 v[92:93], v[84:85], v[8:9], v[56:57]
	v_pk_fma_f32 v[94:95], v[86:87], v[10:11], v[58:59]
	v_pk_fma_f32 v[96:97], v[84:85], v[12:13], v[56:57]
	v_pk_fma_f32 v[98:99], v[86:87], v[14:15], v[58:59]
	v_cvt_pk_bf16_f32 v106, v88, v89
	v_cvt_pk_bf16_f32 v107, v90, v91
	v_cvt_pk_bf16_f32 v108, v92, v93
	v_cvt_pk_bf16_f32 v109, v94, v95
	v_cvt_pk_bf16_f32 v110, v96, v97
	v_cvt_pk_bf16_f32 v111, v98, v99
	global_store_dwordx2 v2, v[106:107], s[6:7]
	global_store_dwordx2 v2, v[108:109], s[8:9]
	global_store_dwordx2 v2, v[110:111], s[10:11]
	s_add_u32 s6, s6, 0x1000
	s_addc_u32 s7, s7, 0
	s_add_u32 s8, s8, 0x1000
	s_addc_u32 s9, s9, 0
	s_add_u32 s10, s10, 0x1000
	s_addc_u32 s11, s11, 0
	s_waitcnt vmcnt(43)
	v_sub_f32_e32 v84, v56, v60
	v_sub_f32_e32 v85, v57, v61
	v_sub_f32_e32 v86, v58, v62
	v_sub_f32_e32 v87, v59, v63
	v_pk_fma_f32 v[88:89], v[84:85], v[4:5], v[60:61]
	v_pk_fma_f32 v[90:91], v[86:87], v[6:7], v[62:63]
	v_pk_fma_f32 v[92:93], v[84:85], v[8:9], v[60:61]
	v_pk_fma_f32 v[94:95], v[86:87], v[10:11], v[62:63]
	v_pk_fma_f32 v[96:97], v[84:85], v[12:13], v[60:61]
	v_pk_fma_f32 v[98:99], v[86:87], v[14:15], v[62:63]
	v_cvt_pk_bf16_f32 v100, v88, v89
	v_cvt_pk_bf16_f32 v101, v90, v91
	v_cvt_pk_bf16_f32 v102, v92, v93
	v_cvt_pk_bf16_f32 v103, v94, v95
	v_cvt_pk_bf16_f32 v104, v96, v97
	v_cvt_pk_bf16_f32 v105, v98, v99
	global_store_dwordx2 v2, v[100:101], s[6:7]
	global_store_dwordx2 v2, v[102:103], s[8:9]
	global_store_dwordx2 v2, v[104:105], s[10:11]
	s_add_u32 s6, s6, 0x1000
	s_addc_u32 s7, s7, 0
	s_add_u32 s8, s8, 0x1000
	s_addc_u32 s9, s9, 0
	s_add_u32 s10, s10, 0x1000
	s_addc_u32 s11, s11, 0
	s_waitcnt vmcnt(45)
	v_sub_f32_e32 v84, v60, v64
	v_sub_f32_e32 v85, v61, v65
	v_sub_f32_e32 v86, v62, v66
	v_sub_f32_e32 v87, v63, v67
	v_pk_fma_f32 v[88:89], v[84:85], v[4:5], v[64:65]
	v_pk_fma_f32 v[90:91], v[86:87], v[6:7], v[66:67]
	v_pk_fma_f32 v[92:93], v[84:85], v[8:9], v[64:65]
	v_pk_fma_f32 v[94:95], v[86:87], v[10:11], v[66:67]
	v_pk_fma_f32 v[96:97], v[84:85], v[12:13], v[64:65]
	v_pk_fma_f32 v[98:99], v[86:87], v[14:15], v[66:67]
	v_cvt_pk_bf16_f32 v106, v88, v89
	v_cvt_pk_bf16_f32 v107, v90, v91
	v_cvt_pk_bf16_f32 v108, v92, v93
	v_cvt_pk_bf16_f32 v109, v94, v95
	v_cvt_pk_bf16_f32 v110, v96, v97
	v_cvt_pk_bf16_f32 v111, v98, v99
	global_store_dwordx2 v2, v[106:107], s[6:7]
	global_store_dwordx2 v2, v[108:109], s[8:9]
	global_store_dwordx2 v2, v[110:111], s[10:11]
	s_add_u32 s6, s6, 0x1000
	s_addc_u32 s7, s7, 0
	s_add_u32 s8, s8, 0x1000
	s_addc_u32 s9, s9, 0
	s_add_u32 s10, s10, 0x1000
	s_addc_u32 s11, s11, 0
	s_waitcnt vmcnt(47)
	v_sub_f32_e32 v84, v64, v68
	v_sub_f32_e32 v85, v65, v69
	v_sub_f32_e32 v86, v66, v70
	v_sub_f32_e32 v87, v67, v71
	v_pk_fma_f32 v[88:89], v[84:85], v[4:5], v[68:69]
	v_pk_fma_f32 v[90:91], v[86:87], v[6:7], v[70:71]
	v_pk_fma_f32 v[92:93], v[84:85], v[8:9], v[68:69]
	v_pk_fma_f32 v[94:95], v[86:87], v[10:11], v[70:71]
	v_pk_fma_f32 v[96:97], v[84:85], v[12:13], v[68:69]
	v_pk_fma_f32 v[98:99], v[86:87], v[14:15], v[70:71]
	v_cvt_pk_bf16_f32 v100, v88, v89
	v_cvt_pk_bf16_f32 v101, v90, v91
	v_cvt_pk_bf16_f32 v102, v92, v93
	v_cvt_pk_bf16_f32 v103, v94, v95
	v_cvt_pk_bf16_f32 v104, v96, v97
	v_cvt_pk_bf16_f32 v105, v98, v99
	global_store_dwordx2 v2, v[100:101], s[6:7]
	global_store_dwordx2 v2, v[102:103], s[8:9]
	global_store_dwordx2 v2, v[104:105], s[10:11]
	s_add_u32 s6, s6, 0x1000
	s_addc_u32 s7, s7, 0
	s_add_u32 s8, s8, 0x1000
	s_addc_u32 s9, s9, 0
	s_add_u32 s10, s10, 0x1000
	s_addc_u32 s11, s11, 0
	s_waitcnt vmcnt(49)
	v_sub_f32_e32 v84, v68, v72
	v_sub_f32_e32 v85, v69, v73
	v_sub_f32_e32 v86, v70, v74
	v_sub_f32_e32 v87, v71, v75
	v_pk_fma_f32 v[88:89], v[84:85], v[4:5], v[72:73]
	v_pk_fma_f32 v[90:91], v[86:87], v[6:7], v[74:75]
	v_pk_fma_f32 v[92:93], v[84:85], v[8:9], v[72:73]
	v_pk_fma_f32 v[94:95], v[86:87], v[10:11], v[74:75]
	v_pk_fma_f32 v[96:97], v[84:85], v[12:13], v[72:73]
	v_pk_fma_f32 v[98:99], v[86:87], v[14:15], v[74:75]
	v_cvt_pk_bf16_f32 v106, v88, v89
	v_cvt_pk_bf16_f32 v107, v90, v91
	v_cvt_pk_bf16_f32 v108, v92, v93
	v_cvt_pk_bf16_f32 v109, v94, v95
	v_cvt_pk_bf16_f32 v110, v96, v97
	v_cvt_pk_bf16_f32 v111, v98, v99
	global_store_dwordx2 v2, v[106:107], s[6:7]
	global_store_dwordx2 v2, v[108:109], s[8:9]
	global_store_dwordx2 v2, v[110:111], s[10:11]
	s_add_u32 s6, s6, 0x1000
	s_addc_u32 s7, s7, 0
	s_add_u32 s8, s8, 0x1000
	s_addc_u32 s9, s9, 0
	s_add_u32 s10, s10, 0x1000
	s_addc_u32 s11, s11, 0
	s_waitcnt vmcnt(51)
	v_sub_f32_e32 v84, v72, v76
	v_sub_f32_e32 v85, v73, v77
	v_sub_f32_e32 v86, v74, v78
	v_sub_f32_e32 v87, v75, v79
	v_pk_fma_f32 v[88:89], v[84:85], v[4:5], v[76:77]
	v_pk_fma_f32 v[90:91], v[86:87], v[6:7], v[78:79]
	v_pk_fma_f32 v[92:93], v[84:85], v[8:9], v[76:77]
	v_pk_fma_f32 v[94:95], v[86:87], v[10:11], v[78:79]
	v_pk_fma_f32 v[96:97], v[84:85], v[12:13], v[76:77]
	v_pk_fma_f32 v[98:99], v[86:87], v[14:15], v[78:79]
	v_cvt_pk_bf16_f32 v100, v88, v89
	v_cvt_pk_bf16_f32 v101, v90, v91
	v_cvt_pk_bf16_f32 v102, v92, v93
	v_cvt_pk_bf16_f32 v103, v94, v95
	v_cvt_pk_bf16_f32 v104, v96, v97
	v_cvt_pk_bf16_f32 v105, v98, v99
	global_store_dwordx2 v2, v[100:101], s[6:7]
	global_store_dwordx2 v2, v[102:103], s[8:9]
	global_store_dwordx2 v2, v[104:105], s[10:11]
	s_add_u32 s6, s6, 0x1000
	s_addc_u32 s7, s7, 0
	s_add_u32 s8, s8, 0x1000
	s_addc_u32 s9, s9, 0
	s_add_u32 s10, s10, 0x1000
	s_addc_u32 s11, s11, 0
	s_waitcnt vmcnt(53)
	v_sub_f32_e32 v84, v76, v80
	v_sub_f32_e32 v85, v77, v81
	v_sub_f32_e32 v86, v78, v82
	v_sub_f32_e32 v87, v79, v83
	v_pk_fma_f32 v[88:89], v[84:85], v[4:5], v[80:81]
	v_pk_fma_f32 v[90:91], v[86:87], v[6:7], v[82:83]
	v_pk_fma_f32 v[92:93], v[84:85], v[8:9], v[80:81]
	v_pk_fma_f32 v[94:95], v[86:87], v[10:11], v[82:83]
	v_pk_fma_f32 v[96:97], v[84:85], v[12:13], v[80:81]
	v_pk_fma_f32 v[98:99], v[86:87], v[14:15], v[82:83]
	v_cvt_pk_bf16_f32 v106, v88, v89
	v_cvt_pk_bf16_f32 v107, v90, v91
	v_cvt_pk_bf16_f32 v108, v92, v93
	v_cvt_pk_bf16_f32 v109, v94, v95
	v_cvt_pk_bf16_f32 v110, v96, v97
	v_cvt_pk_bf16_f32 v111, v98, v99
	global_store_dwordx2 v2, v[106:107], s[6:7]
	global_store_dwordx2 v2, v[108:109], s[8:9]
	global_store_dwordx2 v2, v[110:111], s[10:11]
	s_add_u32 s6, s6, 0x1000
	s_addc_u32 s7, s7, 0
	s_add_u32 s8, s8, 0x1000
	s_addc_u32 s9, s9, 0
	s_add_u32 s10, s10, 0x1000
	s_addc_u32 s11, s11, 0
	v_mov_b32_e32 v16, v80
	v_mov_b32_e32 v17, v81
	v_mov_b32_e32 v18, v82
	v_mov_b32_e32 v19, v83
	global_load_dwordx4 v[52:55], v1, s[4:5] nt
	s_add_u32 s4, s4, 0x2000
	s_addc_u32 s5, s5, 0
	global_load_dwordx4 v[56:59], v1, s[4:5] nt
	s_add_u32 s4, s4, 0x2000
	s_addc_u32 s5, s5, 0
	global_load_dwordx4 v[60:63], v1, s[4:5] nt
	s_add_u32 s4, s4, 0x2000
	s_addc_u32 s5, s5, 0
	global_load_dwordx4 v[64:67], v1, s[4:5] nt
	s_add_u32 s4, s4, 0x2000
	s_addc_u32 s5, s5, 0
	global_load_dwordx4 v[68:71], v1, s[4:5] nt
	s_add_u32 s4, s4, 0x2000
	s_addc_u32 s5, s5, 0
	global_load_dwordx4 v[72:75], v1, s[4:5] nt
	s_add_u32 s4, s4, 0x2000
	s_addc_u32 s5, s5, 0
	global_load_dwordx4 v[76:79], v1, s[4:5] nt
	s_add_u32 s4, s4, 0x2000
	s_addc_u32 s5, s5, 0
	global_load_dwordx4 v[80:83], v1, s[4:5] nt
	s_add_u32 s4, s4, 0x2000
	s_addc_u32 s5, s5, 0
	s_waitcnt vmcnt(39)
	v_sub_f32_e32 v84, v16, v20
	v_sub_f32_e32 v85, v17, v21
	v_sub_f32_e32 v86, v18, v22
	v_sub_f32_e32 v87, v19, v23
	v_pk_fma_f32 v[88:89], v[84:85], v[4:5], v[20:21]
	v_pk_fma_f32 v[90:91], v[86:87], v[6:7], v[22:23]
	v_pk_fma_f32 v[92:93], v[84:85], v[8:9], v[20:21]
	v_pk_fma_f32 v[94:95], v[86:87], v[10:11], v[22:23]
	v_pk_fma_f32 v[96:97], v[84:85], v[12:13], v[20:21]
	v_pk_fma_f32 v[98:99], v[86:87], v[14:15], v[22:23]
	v_cvt_pk_bf16_f32 v100, v88, v89
	v_cvt_pk_bf16_f32 v101, v90, v91
	v_cvt_pk_bf16_f32 v102, v92, v93
	v_cvt_pk_bf16_f32 v103, v94, v95
	v_cvt_pk_bf16_f32 v104, v96, v97
	v_cvt_pk_bf16_f32 v105, v98, v99
	global_store_dwordx2 v2, v[100:101], s[6:7]
	global_store_dwordx2 v2, v[102:103], s[8:9]
	global_store_dwordx2 v2, v[104:105], s[10:11]
	s_add_u32 s6, s6, 0x1000
	s_addc_u32 s7, s7, 0
	s_add_u32 s8, s8, 0x1000
	s_addc_u32 s9, s9, 0
	s_add_u32 s10, s10, 0x1000
	s_addc_u32 s11, s11, 0
	s_waitcnt vmcnt(41)
	v_sub_f32_e32 v84, v20, v24
	v_sub_f32_e32 v85, v21, v25
	v_sub_f32_e32 v86, v22, v26
	v_sub_f32_e32 v87, v23, v27
	v_pk_fma_f32 v[88:89], v[84:85], v[4:5], v[24:25]
	v_pk_fma_f32 v[90:91], v[86:87], v[6:7], v[26:27]
	v_pk_fma_f32 v[92:93], v[84:85], v[8:9], v[24:25]
	v_pk_fma_f32 v[94:95], v[86:87], v[10:11], v[26:27]
	v_pk_fma_f32 v[96:97], v[84:85], v[12:13], v[24:25]
	v_pk_fma_f32 v[98:99], v[86:87], v[14:15], v[26:27]
	v_cvt_pk_bf16_f32 v106, v88, v89
	v_cvt_pk_bf16_f32 v107, v90, v91
	v_cvt_pk_bf16_f32 v108, v92, v93
	v_cvt_pk_bf16_f32 v109, v94, v95
	v_cvt_pk_bf16_f32 v110, v96, v97
	v_cvt_pk_bf16_f32 v111, v98, v99
	global_store_dwordx2 v2, v[106:107], s[6:7]
	global_store_dwordx2 v2, v[108:109], s[8:9]
	global_store_dwordx2 v2, v[110:111], s[10:11]
	s_add_u32 s6, s6, 0x1000
	s_addc_u32 s7, s7, 0
	s_add_u32 s8, s8, 0x1000
	s_addc_u32 s9, s9, 0
	s_add_u32 s10, s10, 0x1000
	s_addc_u32 s11, s11, 0
	s_waitcnt vmcnt(43)
	v_sub_f32_e32 v84, v24, v28
	v_sub_f32_e32 v85, v25, v29
	v_sub_f32_e32 v86, v26, v30
	v_sub_f32_e32 v87, v27, v31
	v_pk_fma_f32 v[88:89], v[84:85], v[4:5], v[28:29]
	v_pk_fma_f32 v[90:91], v[86:87], v[6:7], v[30:31]
	v_pk_fma_f32 v[92:93], v[84:85], v[8:9], v[28:29]
	v_pk_fma_f32 v[94:95], v[86:87], v[10:11], v[30:31]
	v_pk_fma_f32 v[96:97], v[84:85], v[12:13], v[28:29]
	v_pk_fma_f32 v[98:99], v[86:87], v[14:15], v[30:31]
	v_cvt_pk_bf16_f32 v100, v88, v89
	v_cvt_pk_bf16_f32 v101, v90, v91
	v_cvt_pk_bf16_f32 v102, v92, v93
	v_cvt_pk_bf16_f32 v103, v94, v95
	v_cvt_pk_bf16_f32 v104, v96, v97
	v_cvt_pk_bf16_f32 v105, v98, v99
	global_store_dwordx2 v2, v[100:101], s[6:7]
	global_store_dwordx2 v2, v[102:103], s[8:9]
	global_store_dwordx2 v2, v[104:105], s[10:11]
	s_add_u32 s6, s6, 0x1000
	s_addc_u32 s7, s7, 0
	s_add_u32 s8, s8, 0x1000
	s_addc_u32 s9, s9, 0
	s_add_u32 s10, s10, 0x1000
	s_addc_u32 s11, s11, 0
	s_waitcnt vmcnt(45)
	v_sub_f32_e32 v84, v28, v32
	v_sub_f32_e32 v85, v29, v33
	v_sub_f32_e32 v86, v30, v34
	v_sub_f32_e32 v87, v31, v35
	v_pk_fma_f32 v[88:89], v[84:85], v[4:5], v[32:33]
	v_pk_fma_f32 v[90:91], v[86:87], v[6:7], v[34:35]
	v_pk_fma_f32 v[92:93], v[84:85], v[8:9], v[32:33]
	v_pk_fma_f32 v[94:95], v[86:87], v[10:11], v[34:35]
	v_pk_fma_f32 v[96:97], v[84:85], v[12:13], v[32:33]
	v_pk_fma_f32 v[98:99], v[86:87], v[14:15], v[34:35]
	v_cvt_pk_bf16_f32 v106, v88, v89
	v_cvt_pk_bf16_f32 v107, v90, v91
	v_cvt_pk_bf16_f32 v108, v92, v93
	v_cvt_pk_bf16_f32 v109, v94, v95
	v_cvt_pk_bf16_f32 v110, v96, v97
	v_cvt_pk_bf16_f32 v111, v98, v99
	global_store_dwordx2 v2, v[106:107], s[6:7]
	global_store_dwordx2 v2, v[108:109], s[8:9]
	global_store_dwordx2 v2, v[110:111], s[10:11]
	s_add_u32 s6, s6, 0x1000
	s_addc_u32 s7, s7, 0
	s_add_u32 s8, s8, 0x1000
	s_addc_u32 s9, s9, 0
	s_add_u32 s10, s10, 0x1000
	s_addc_u32 s11, s11, 0
	s_waitcnt vmcnt(47)
	v_sub_f32_e32 v84, v32, v36
	v_sub_f32_e32 v85, v33, v37
	v_sub_f32_e32 v86, v34, v38
	v_sub_f32_e32 v87, v35, v39
	v_pk_fma_f32 v[88:89], v[84:85], v[4:5], v[36:37]
	v_pk_fma_f32 v[90:91], v[86:87], v[6:7], v[38:39]
	v_pk_fma_f32 v[92:93], v[84:85], v[8:9], v[36:37]
	v_pk_fma_f32 v[94:95], v[86:87], v[10:11], v[38:39]
	v_pk_fma_f32 v[96:97], v[84:85], v[12:13], v[36:37]
	v_pk_fma_f32 v[98:99], v[86:87], v[14:15], v[38:39]
	v_cvt_pk_bf16_f32 v100, v88, v89
	v_cvt_pk_bf16_f32 v101, v90, v91
	v_cvt_pk_bf16_f32 v102, v92, v93
	v_cvt_pk_bf16_f32 v103, v94, v95
	v_cvt_pk_bf16_f32 v104, v96, v97
	v_cvt_pk_bf16_f32 v105, v98, v99
	global_store_dwordx2 v2, v[100:101], s[6:7]
	global_store_dwordx2 v2, v[102:103], s[8:9]
	global_store_dwordx2 v2, v[104:105], s[10:11]
	s_add_u32 s6, s6, 0x1000
	s_addc_u32 s7, s7, 0
	s_add_u32 s8, s8, 0x1000
	s_addc_u32 s9, s9, 0
	s_add_u32 s10, s10, 0x1000
	s_addc_u32 s11, s11, 0
	s_waitcnt vmcnt(49)
	v_sub_f32_e32 v84, v36, v40
	v_sub_f32_e32 v85, v37, v41
	v_sub_f32_e32 v86, v38, v42
	v_sub_f32_e32 v87, v39, v43
	v_pk_fma_f32 v[88:89], v[84:85], v[4:5], v[40:41]
	v_pk_fma_f32 v[90:91], v[86:87], v[6:7], v[42:43]
	v_pk_fma_f32 v[92:93], v[84:85], v[8:9], v[40:41]
	v_pk_fma_f32 v[94:95], v[86:87], v[10:11], v[42:43]
	v_pk_fma_f32 v[96:97], v[84:85], v[12:13], v[40:41]
	v_pk_fma_f32 v[98:99], v[86:87], v[14:15], v[42:43]
	v_cvt_pk_bf16_f32 v106, v88, v89
	v_cvt_pk_bf16_f32 v107, v90, v91
	v_cvt_pk_bf16_f32 v108, v92, v93
	v_cvt_pk_bf16_f32 v109, v94, v95
	v_cvt_pk_bf16_f32 v110, v96, v97
	v_cvt_pk_bf16_f32 v111, v98, v99
	global_store_dwordx2 v2, v[106:107], s[6:7]
	global_store_dwordx2 v2, v[108:109], s[8:9]
	global_store_dwordx2 v2, v[110:111], s[10:11]
	s_add_u32 s6, s6, 0x1000
	s_addc_u32 s7, s7, 0
	s_add_u32 s8, s8, 0x1000
	s_addc_u32 s9, s9, 0
	s_add_u32 s10, s10, 0x1000
	s_addc_u32 s11, s11, 0
	s_waitcnt vmcnt(51)
	v_sub_f32_e32 v84, v40, v44
	v_sub_f32_e32 v85, v41, v45
	v_sub_f32_e32 v86, v42, v46
	v_sub_f32_e32 v87, v43, v47
	v_pk_fma_f32 v[88:89], v[84:85], v[4:5], v[44:45]
	v_pk_fma_f32 v[90:91], v[86:87], v[6:7], v[46:47]
	v_pk_fma_f32 v[92:93], v[84:85], v[8:9], v[44:45]
	v_pk_fma_f32 v[94:95], v[86:87], v[10:11], v[46:47]
	v_pk_fma_f32 v[96:97], v[84:85], v[12:13], v[44:45]
	v_pk_fma_f32 v[98:99], v[86:87], v[14:15], v[46:47]
	v_cvt_pk_bf16_f32 v100, v88, v89
	v_cvt_pk_bf16_f32 v101, v90, v91
	v_cvt_pk_bf16_f32 v102, v92, v93
	v_cvt_pk_bf16_f32 v103, v94, v95
	v_cvt_pk_bf16_f32 v104, v96, v97
	v_cvt_pk_bf16_f32 v105, v98, v99
	global_store_dwordx2 v2, v[100:101], s[6:7]
	global_store_dwordx2 v2, v[102:103], s[8:9]
	global_store_dwordx2 v2, v[104:105], s[10:11]
	s_add_u32 s6, s6, 0x1000
	s_addc_u32 s7, s7, 0
	s_add_u32 s8, s8, 0x1000
	s_addc_u32 s9, s9, 0
	s_add_u32 s10, s10, 0x1000
	s_addc_u32 s11, s11, 0
	s_waitcnt vmcnt(53)
	v_sub_f32_e32 v84, v44, v48
	v_sub_f32_e32 v85, v45, v49
	v_sub_f32_e32 v86, v46, v50
	v_sub_f32_e32 v87, v47, v51
	v_pk_fma_f32 v[88:89], v[84:85], v[4:5], v[48:49]
	v_pk_fma_f32 v[90:91], v[86:87], v[6:7], v[50:51]
	v_pk_fma_f32 v[92:93], v[84:85], v[8:9], v[48:49]
	v_pk_fma_f32 v[94:95], v[86:87], v[10:11], v[50:51]
	v_pk_fma_f32 v[96:97], v[84:85], v[12:13], v[48:49]
	v_pk_fma_f32 v[98:99], v[86:87], v[14:15], v[50:51]
	v_cvt_pk_bf16_f32 v106, v88, v89
	v_cvt_pk_bf16_f32 v107, v90, v91
	v_cvt_pk_bf16_f32 v108, v92, v93
	v_cvt_pk_bf16_f32 v109, v94, v95
	v_cvt_pk_bf16_f32 v110, v96, v97
	v_cvt_pk_bf16_f32 v111, v98, v99
	global_store_dwordx2 v2, v[106:107], s[6:7]
	global_store_dwordx2 v2, v[108:109], s[8:9]
	global_store_dwordx2 v2, v[110:111], s[10:11]
	s_add_u32 s6, s6, 0x1000
	s_addc_u32 s7, s7, 0
	s_add_u32 s8, s8, 0x1000
	s_addc_u32 s9, s9, 0
	s_add_u32 s10, s10, 0x1000
	s_addc_u32 s11, s11, 0
	v_mov_b32_e32 v16, v48
	v_mov_b32_e32 v17, v49
	v_mov_b32_e32 v18, v50
	v_mov_b32_e32 v19, v51
	global_load_dwordx4 v[20:23], v1, s[4:5] nt
	s_add_u32 s4, s4, 0x2000
	s_addc_u32 s5, s5, 0
	global_load_dwordx4 v[24:27], v1, s[4:5] nt
	s_add_u32 s4, s4, 0x2000
	s_addc_u32 s5, s5, 0
	global_load_dwordx4 v[28:31], v1, s[4:5] nt
	s_add_u32 s4, s4, 0x2000
	s_addc_u32 s5, s5, 0
	global_load_dwordx4 v[32:35], v1, s[4:5] nt
	s_add_u32 s4, s4, 0x2000
	s_addc_u32 s5, s5, 0
	global_load_dwordx4 v[36:39], v1, s[4:5] nt
	s_add_u32 s4, s4, 0x2000
	s_addc_u32 s5, s5, 0
	global_load_dwordx4 v[40:43], v1, s[4:5] nt
	s_add_u32 s4, s4, 0x2000
	s_addc_u32 s5, s5, 0
	global_load_dwordx4 v[44:47], v1, s[4:5] nt
	s_add_u32 s4, s4, 0x2000
	s_addc_u32 s5, s5, 0
	global_load_dwordx4 v[48:51], v1, s[4:5] nt
	s_add_u32 s4, s4, 0x2000
	s_addc_u32 s5, s5, 0
	s_waitcnt vmcnt(39)
	v_sub_f32_e32 v84, v16, v52
	v_sub_f32_e32 v85, v17, v53
	v_sub_f32_e32 v86, v18, v54
	v_sub_f32_e32 v87, v19, v55
	v_pk_fma_f32 v[88:89], v[84:85], v[4:5], v[52:53]
	v_pk_fma_f32 v[90:91], v[86:87], v[6:7], v[54:55]
	v_pk_fma_f32 v[92:93], v[84:85], v[8:9], v[52:53]
	v_pk_fma_f32 v[94:95], v[86:87], v[10:11], v[54:55]
	v_pk_fma_f32 v[96:97], v[84:85], v[12:13], v[52:53]
	v_pk_fma_f32 v[98:99], v[86:87], v[14:15], v[54:55]
	v_cvt_pk_bf16_f32 v100, v88, v89
	v_cvt_pk_bf16_f32 v101, v90, v91
	v_cvt_pk_bf16_f32 v102, v92, v93
	v_cvt_pk_bf16_f32 v103, v94, v95
	v_cvt_pk_bf16_f32 v104, v96, v97
	v_cvt_pk_bf16_f32 v105, v98, v99
	global_store_dwordx2 v2, v[100:101], s[6:7]
	global_store_dwordx2 v2, v[102:103], s[8:9]
	global_store_dwordx2 v2, v[104:105], s[10:11]
	s_add_u32 s6, s6, 0x1000
	s_addc_u32 s7, s7, 0
	s_add_u32 s8, s8, 0x1000
	s_addc_u32 s9, s9, 0
	s_add_u32 s10, s10, 0x1000
	s_addc_u32 s11, s11, 0
	s_waitcnt vmcnt(41)
	v_sub_f32_e32 v84, v52, v56
	v_sub_f32_e32 v85, v53, v57
	v_sub_f32_e32 v86, v54, v58
	v_sub_f32_e32 v87, v55, v59
	v_pk_fma_f32 v[88:89], v[84:85], v[4:5], v[56:57]
	v_pk_fma_f32 v[90:91], v[86:87], v[6:7], v[58:59]
	v_pk_fma_f32 v[92:93], v[84:85], v[8:9], v[56:57]
	v_pk_fma_f32 v[94:95], v[86:87], v[10:11], v[58:59]
	v_pk_fma_f32 v[96:97], v[84:85], v[12:13], v[56:57]
	v_pk_fma_f32 v[98:99], v[86:87], v[14:15], v[58:59]
	v_cvt_pk_bf16_f32 v106, v88, v89
	v_cvt_pk_bf16_f32 v107, v90, v91
	v_cvt_pk_bf16_f32 v108, v92, v93
	v_cvt_pk_bf16_f32 v109, v94, v95
	v_cvt_pk_bf16_f32 v110, v96, v97
	v_cvt_pk_bf16_f32 v111, v98, v99
	global_store_dwordx2 v2, v[106:107], s[6:7]
	global_store_dwordx2 v2, v[108:109], s[8:9]
	global_store_dwordx2 v2, v[110:111], s[10:11]
	s_add_u32 s6, s6, 0x1000
	s_addc_u32 s7, s7, 0
	s_add_u32 s8, s8, 0x1000
	s_addc_u32 s9, s9, 0
	s_add_u32 s10, s10, 0x1000
	s_addc_u32 s11, s11, 0
	s_waitcnt vmcnt(43)
	v_sub_f32_e32 v84, v56, v60
	v_sub_f32_e32 v85, v57, v61
	v_sub_f32_e32 v86, v58, v62
	v_sub_f32_e32 v87, v59, v63
	v_pk_fma_f32 v[88:89], v[84:85], v[4:5], v[60:61]
	v_pk_fma_f32 v[90:91], v[86:87], v[6:7], v[62:63]
	v_pk_fma_f32 v[92:93], v[84:85], v[8:9], v[60:61]
	v_pk_fma_f32 v[94:95], v[86:87], v[10:11], v[62:63]
	v_pk_fma_f32 v[96:97], v[84:85], v[12:13], v[60:61]
	v_pk_fma_f32 v[98:99], v[86:87], v[14:15], v[62:63]
	v_cvt_pk_bf16_f32 v100, v88, v89
	v_cvt_pk_bf16_f32 v101, v90, v91
	v_cvt_pk_bf16_f32 v102, v92, v93
	v_cvt_pk_bf16_f32 v103, v94, v95
	v_cvt_pk_bf16_f32 v104, v96, v97
	v_cvt_pk_bf16_f32 v105, v98, v99
	global_store_dwordx2 v2, v[100:101], s[6:7]
	global_store_dwordx2 v2, v[102:103], s[8:9]
	global_store_dwordx2 v2, v[104:105], s[10:11]
	s_add_u32 s6, s6, 0x1000
	s_addc_u32 s7, s7, 0
	s_add_u32 s8, s8, 0x1000
	s_addc_u32 s9, s9, 0
	s_add_u32 s10, s10, 0x1000
	s_addc_u32 s11, s11, 0
	s_waitcnt vmcnt(45)
	v_sub_f32_e32 v84, v60, v64
	v_sub_f32_e32 v85, v61, v65
	v_sub_f32_e32 v86, v62, v66
	v_sub_f32_e32 v87, v63, v67
	v_pk_fma_f32 v[88:89], v[84:85], v[4:5], v[64:65]
	v_pk_fma_f32 v[90:91], v[86:87], v[6:7], v[66:67]
	v_pk_fma_f32 v[92:93], v[84:85], v[8:9], v[64:65]
	v_pk_fma_f32 v[94:95], v[86:87], v[10:11], v[66:67]
	v_pk_fma_f32 v[96:97], v[84:85], v[12:13], v[64:65]
	v_pk_fma_f32 v[98:99], v[86:87], v[14:15], v[66:67]
	v_cvt_pk_bf16_f32 v106, v88, v89
	v_cvt_pk_bf16_f32 v107, v90, v91
	v_cvt_pk_bf16_f32 v108, v92, v93
	v_cvt_pk_bf16_f32 v109, v94, v95
	v_cvt_pk_bf16_f32 v110, v96, v97
	v_cvt_pk_bf16_f32 v111, v98, v99
	global_store_dwordx2 v2, v[106:107], s[6:7]
	global_store_dwordx2 v2, v[108:109], s[8:9]
	global_store_dwordx2 v2, v[110:111], s[10:11]
	s_add_u32 s6, s6, 0x1000
	s_addc_u32 s7, s7, 0
	s_add_u32 s8, s8, 0x1000
	s_addc_u32 s9, s9, 0
	s_add_u32 s10, s10, 0x1000
	s_addc_u32 s11, s11, 0
	s_waitcnt vmcnt(47)
	v_sub_f32_e32 v84, v64, v68
	v_sub_f32_e32 v85, v65, v69
	v_sub_f32_e32 v86, v66, v70
	v_sub_f32_e32 v87, v67, v71
	v_pk_fma_f32 v[88:89], v[84:85], v[4:5], v[68:69]
	v_pk_fma_f32 v[90:91], v[86:87], v[6:7], v[70:71]
	v_pk_fma_f32 v[92:93], v[84:85], v[8:9], v[68:69]
	v_pk_fma_f32 v[94:95], v[86:87], v[10:11], v[70:71]
	v_pk_fma_f32 v[96:97], v[84:85], v[12:13], v[68:69]
	v_pk_fma_f32 v[98:99], v[86:87], v[14:15], v[70:71]
	v_cvt_pk_bf16_f32 v100, v88, v89
	v_cvt_pk_bf16_f32 v101, v90, v91
	v_cvt_pk_bf16_f32 v102, v92, v93
	v_cvt_pk_bf16_f32 v103, v94, v95
	v_cvt_pk_bf16_f32 v104, v96, v97
	v_cvt_pk_bf16_f32 v105, v98, v99
	global_store_dwordx2 v2, v[100:101], s[6:7]
	global_store_dwordx2 v2, v[102:103], s[8:9]
	global_store_dwordx2 v2, v[104:105], s[10:11]
	s_add_u32 s6, s6, 0x1000
	s_addc_u32 s7, s7, 0
	s_add_u32 s8, s8, 0x1000
	s_addc_u32 s9, s9, 0
	s_add_u32 s10, s10, 0x1000
	s_addc_u32 s11, s11, 0
	s_waitcnt vmcnt(49)
	v_sub_f32_e32 v84, v68, v72
	v_sub_f32_e32 v85, v69, v73
	v_sub_f32_e32 v86, v70, v74
	v_sub_f32_e32 v87, v71, v75
	v_pk_fma_f32 v[88:89], v[84:85], v[4:5], v[72:73]
	v_pk_fma_f32 v[90:91], v[86:87], v[6:7], v[74:75]
	v_pk_fma_f32 v[92:93], v[84:85], v[8:9], v[72:73]
	v_pk_fma_f32 v[94:95], v[86:87], v[10:11], v[74:75]
	v_pk_fma_f32 v[96:97], v[84:85], v[12:13], v[72:73]
	v_pk_fma_f32 v[98:99], v[86:87], v[14:15], v[74:75]
	v_cvt_pk_bf16_f32 v106, v88, v89
	v_cvt_pk_bf16_f32 v107, v90, v91
	v_cvt_pk_bf16_f32 v108, v92, v93
	v_cvt_pk_bf16_f32 v109, v94, v95
	v_cvt_pk_bf16_f32 v110, v96, v97
	v_cvt_pk_bf16_f32 v111, v98, v99
	global_store_dwordx2 v2, v[106:107], s[6:7]
	global_store_dwordx2 v2, v[108:109], s[8:9]
	global_store_dwordx2 v2, v[110:111], s[10:11]
	s_add_u32 s6, s6, 0x1000
	s_addc_u32 s7, s7, 0
	s_add_u32 s8, s8, 0x1000
	s_addc_u32 s9, s9, 0
	s_add_u32 s10, s10, 0x1000
	s_addc_u32 s11, s11, 0
	s_waitcnt vmcnt(51)
	v_sub_f32_e32 v84, v72, v76
	v_sub_f32_e32 v85, v73, v77
	v_sub_f32_e32 v86, v74, v78
	v_sub_f32_e32 v87, v75, v79
	v_pk_fma_f32 v[88:89], v[84:85], v[4:5], v[76:77]
	v_pk_fma_f32 v[90:91], v[86:87], v[6:7], v[78:79]
	v_pk_fma_f32 v[92:93], v[84:85], v[8:9], v[76:77]
	v_pk_fma_f32 v[94:95], v[86:87], v[10:11], v[78:79]
	v_pk_fma_f32 v[96:97], v[84:85], v[12:13], v[76:77]
	v_pk_fma_f32 v[98:99], v[86:87], v[14:15], v[78:79]
	v_cvt_pk_bf16_f32 v100, v88, v89
	v_cvt_pk_bf16_f32 v101, v90, v91
	v_cvt_pk_bf16_f32 v102, v92, v93
	v_cvt_pk_bf16_f32 v103, v94, v95
	v_cvt_pk_bf16_f32 v104, v96, v97
	v_cvt_pk_bf16_f32 v105, v98, v99
	global_store_dwordx2 v2, v[100:101], s[6:7]
	global_store_dwordx2 v2, v[102:103], s[8:9]
	global_store_dwordx2 v2, v[104:105], s[10:11]
	s_add_u32 s6, s6, 0x1000
	s_addc_u32 s7, s7, 0
	s_add_u32 s8, s8, 0x1000
	s_addc_u32 s9, s9, 0
	s_add_u32 s10, s10, 0x1000
	s_addc_u32 s11, s11, 0
	s_waitcnt vmcnt(53)
	v_sub_f32_e32 v84, v76, v80
	v_sub_f32_e32 v85, v77, v81
	v_sub_f32_e32 v86, v78, v82
	v_sub_f32_e32 v87, v79, v83
	v_pk_fma_f32 v[88:89], v[84:85], v[4:5], v[80:81]
	v_pk_fma_f32 v[90:91], v[86:87], v[6:7], v[82:83]
	v_pk_fma_f32 v[92:93], v[84:85], v[8:9], v[80:81]
	v_pk_fma_f32 v[94:95], v[86:87], v[10:11], v[82:83]
	v_pk_fma_f32 v[96:97], v[84:85], v[12:13], v[80:81]
	v_pk_fma_f32 v[98:99], v[86:87], v[14:15], v[82:83]
	v_cvt_pk_bf16_f32 v106, v88, v89
	v_cvt_pk_bf16_f32 v107, v90, v91
	v_cvt_pk_bf16_f32 v108, v92, v93
	v_cvt_pk_bf16_f32 v109, v94, v95
	v_cvt_pk_bf16_f32 v110, v96, v97
	v_cvt_pk_bf16_f32 v111, v98, v99
	global_store_dwordx2 v2, v[106:107], s[6:7]
	global_store_dwordx2 v2, v[108:109], s[8:9]
	global_store_dwordx2 v2, v[110:111], s[10:11]
	s_add_u32 s6, s6, 0x1000
	s_addc_u32 s7, s7, 0
	s_add_u32 s8, s8, 0x1000
	s_addc_u32 s9, s9, 0
	s_add_u32 s10, s10, 0x1000
	s_addc_u32 s11, s11, 0
	v_mov_b32_e32 v16, v80
	v_mov_b32_e32 v17, v81
	v_mov_b32_e32 v18, v82
	v_mov_b32_e32 v19, v83
	global_load_dwordx4 v[52:55], v1, s[4:5] nt
	s_add_u32 s4, s4, 0x2000
	s_addc_u32 s5, s5, 0
	global_load_dwordx4 v[56:59], v1, s[4:5] nt
	s_add_u32 s4, s4, 0x2000
	s_addc_u32 s5, s5, 0
	global_load_dwordx4 v[60:63], v1, s[4:5] nt
	s_add_u32 s4, s4, 0x2000
	s_addc_u32 s5, s5, 0
	global_load_dwordx4 v[64:67], v1, s[4:5] nt
	s_add_u32 s4, s4, 0x2000
	s_addc_u32 s5, s5, 0
	global_load_dwordx4 v[68:71], v1, s[4:5] nt
	s_add_u32 s4, s4, 0x2000
	s_addc_u32 s5, s5, 0
	global_load_dwordx4 v[72:75], v1, s[4:5] nt
	s_add_u32 s4, s4, 0x2000
	s_addc_u32 s5, s5, 0
	global_load_dwordx4 v[76:79], v1, s[4:5] nt
	s_add_u32 s4, s4, 0x2000
	s_addc_u32 s5, s5, 0
	global_load_dwordx4 v[80:83], v1, s[4:5] nt
	s_add_u32 s4, s4, 0x2000
	s_addc_u32 s5, s5, 0
	s_waitcnt vmcnt(39)
	v_sub_f32_e32 v84, v16, v20
	v_sub_f32_e32 v85, v17, v21
	v_sub_f32_e32 v86, v18, v22
	v_sub_f32_e32 v87, v19, v23
	v_pk_fma_f32 v[88:89], v[84:85], v[4:5], v[20:21]
	v_pk_fma_f32 v[90:91], v[86:87], v[6:7], v[22:23]
	v_pk_fma_f32 v[92:93], v[84:85], v[8:9], v[20:21]
	v_pk_fma_f32 v[94:95], v[86:87], v[10:11], v[22:23]
	v_pk_fma_f32 v[96:97], v[84:85], v[12:13], v[20:21]
	v_pk_fma_f32 v[98:99], v[86:87], v[14:15], v[22:23]
	v_cvt_pk_bf16_f32 v100, v88, v89
	v_cvt_pk_bf16_f32 v101, v90, v91
	v_cvt_pk_bf16_f32 v102, v92, v93
	v_cvt_pk_bf16_f32 v103, v94, v95
	v_cvt_pk_bf16_f32 v104, v96, v97
	v_cvt_pk_bf16_f32 v105, v98, v99
	global_store_dwordx2 v2, v[100:101], s[6:7]
	global_store_dwordx2 v2, v[102:103], s[8:9]
	global_store_dwordx2 v2, v[104:105], s[10:11]
	s_add_u32 s6, s6, 0x1000
	s_addc_u32 s7, s7, 0
	s_add_u32 s8, s8, 0x1000
	s_addc_u32 s9, s9, 0
	s_add_u32 s10, s10, 0x1000
	s_addc_u32 s11, s11, 0
	s_waitcnt vmcnt(41)
	v_sub_f32_e32 v84, v20, v24
	v_sub_f32_e32 v85, v21, v25
	v_sub_f32_e32 v86, v22, v26
	v_sub_f32_e32 v87, v23, v27
	v_pk_fma_f32 v[88:89], v[84:85], v[4:5], v[24:25]
	v_pk_fma_f32 v[90:91], v[86:87], v[6:7], v[26:27]
	v_pk_fma_f32 v[92:93], v[84:85], v[8:9], v[24:25]
	v_pk_fma_f32 v[94:95], v[86:87], v[10:11], v[26:27]
	v_pk_fma_f32 v[96:97], v[84:85], v[12:13], v[24:25]
	v_pk_fma_f32 v[98:99], v[86:87], v[14:15], v[26:27]
	v_cvt_pk_bf16_f32 v106, v88, v89
	v_cvt_pk_bf16_f32 v107, v90, v91
	v_cvt_pk_bf16_f32 v108, v92, v93
	v_cvt_pk_bf16_f32 v109, v94, v95
	v_cvt_pk_bf16_f32 v110, v96, v97
	v_cvt_pk_bf16_f32 v111, v98, v99
	global_store_dwordx2 v2, v[106:107], s[6:7]
	global_store_dwordx2 v2, v[108:109], s[8:9]
	global_store_dwordx2 v2, v[110:111], s[10:11]
	s_add_u32 s6, s6, 0x1000
	s_addc_u32 s7, s7, 0
	s_add_u32 s8, s8, 0x1000
	s_addc_u32 s9, s9, 0
	s_add_u32 s10, s10, 0x1000
	s_addc_u32 s11, s11, 0
	s_waitcnt vmcnt(43)
	v_sub_f32_e32 v84, v24, v28
	v_sub_f32_e32 v85, v25, v29
	v_sub_f32_e32 v86, v26, v30
	v_sub_f32_e32 v87, v27, v31
	v_pk_fma_f32 v[88:89], v[84:85], v[4:5], v[28:29]
	v_pk_fma_f32 v[90:91], v[86:87], v[6:7], v[30:31]
	v_pk_fma_f32 v[92:93], v[84:85], v[8:9], v[28:29]
	v_pk_fma_f32 v[94:95], v[86:87], v[10:11], v[30:31]
	v_pk_fma_f32 v[96:97], v[84:85], v[12:13], v[28:29]
	v_pk_fma_f32 v[98:99], v[86:87], v[14:15], v[30:31]
	v_cvt_pk_bf16_f32 v100, v88, v89
	v_cvt_pk_bf16_f32 v101, v90, v91
	v_cvt_pk_bf16_f32 v102, v92, v93
	v_cvt_pk_bf16_f32 v103, v94, v95
	v_cvt_pk_bf16_f32 v104, v96, v97
	v_cvt_pk_bf16_f32 v105, v98, v99
	global_store_dwordx2 v2, v[100:101], s[6:7]
	global_store_dwordx2 v2, v[102:103], s[8:9]
	global_store_dwordx2 v2, v[104:105], s[10:11]
	s_add_u32 s6, s6, 0x1000
	s_addc_u32 s7, s7, 0
	s_add_u32 s8, s8, 0x1000
	s_addc_u32 s9, s9, 0
	s_add_u32 s10, s10, 0x1000
	s_addc_u32 s11, s11, 0
	s_waitcnt vmcnt(45)
	v_sub_f32_e32 v84, v28, v32
	v_sub_f32_e32 v85, v29, v33
	v_sub_f32_e32 v86, v30, v34
	v_sub_f32_e32 v87, v31, v35
	v_pk_fma_f32 v[88:89], v[84:85], v[4:5], v[32:33]
	v_pk_fma_f32 v[90:91], v[86:87], v[6:7], v[34:35]
	v_pk_fma_f32 v[92:93], v[84:85], v[8:9], v[32:33]
	v_pk_fma_f32 v[94:95], v[86:87], v[10:11], v[34:35]
	v_pk_fma_f32 v[96:97], v[84:85], v[12:13], v[32:33]
	v_pk_fma_f32 v[98:99], v[86:87], v[14:15], v[34:35]
	v_cvt_pk_bf16_f32 v106, v88, v89
	v_cvt_pk_bf16_f32 v107, v90, v91
	v_cvt_pk_bf16_f32 v108, v92, v93
	v_cvt_pk_bf16_f32 v109, v94, v95
	v_cvt_pk_bf16_f32 v110, v96, v97
	v_cvt_pk_bf16_f32 v111, v98, v99
	global_store_dwordx2 v2, v[106:107], s[6:7]
	global_store_dwordx2 v2, v[108:109], s[8:9]
	global_store_dwordx2 v2, v[110:111], s[10:11]
	s_add_u32 s6, s6, 0x1000
	s_addc_u32 s7, s7, 0
	s_add_u32 s8, s8, 0x1000
	s_addc_u32 s9, s9, 0
	s_add_u32 s10, s10, 0x1000
	s_addc_u32 s11, s11, 0
	s_waitcnt vmcnt(47)
	v_sub_f32_e32 v84, v32, v36
	v_sub_f32_e32 v85, v33, v37
	v_sub_f32_e32 v86, v34, v38
	v_sub_f32_e32 v87, v35, v39
	v_pk_fma_f32 v[88:89], v[84:85], v[4:5], v[36:37]
	v_pk_fma_f32 v[90:91], v[86:87], v[6:7], v[38:39]
	v_pk_fma_f32 v[92:93], v[84:85], v[8:9], v[36:37]
	v_pk_fma_f32 v[94:95], v[86:87], v[10:11], v[38:39]
	v_pk_fma_f32 v[96:97], v[84:85], v[12:13], v[36:37]
	v_pk_fma_f32 v[98:99], v[86:87], v[14:15], v[38:39]
	v_cvt_pk_bf16_f32 v100, v88, v89
	v_cvt_pk_bf16_f32 v101, v90, v91
	v_cvt_pk_bf16_f32 v102, v92, v93
	v_cvt_pk_bf16_f32 v103, v94, v95
	v_cvt_pk_bf16_f32 v104, v96, v97
	v_cvt_pk_bf16_f32 v105, v98, v99
	global_store_dwordx2 v2, v[100:101], s[6:7]
	global_store_dwordx2 v2, v[102:103], s[8:9]
	global_store_dwordx2 v2, v[104:105], s[10:11]
	s_add_u32 s6, s6, 0x1000
	s_addc_u32 s7, s7, 0
	s_add_u32 s8, s8, 0x1000
	s_addc_u32 s9, s9, 0
	s_add_u32 s10, s10, 0x1000
	s_addc_u32 s11, s11, 0
	s_waitcnt vmcnt(49)
	v_sub_f32_e32 v84, v36, v40
	v_sub_f32_e32 v85, v37, v41
	v_sub_f32_e32 v86, v38, v42
	v_sub_f32_e32 v87, v39, v43
	v_pk_fma_f32 v[88:89], v[84:85], v[4:5], v[40:41]
	v_pk_fma_f32 v[90:91], v[86:87], v[6:7], v[42:43]
	v_pk_fma_f32 v[92:93], v[84:85], v[8:9], v[40:41]
	v_pk_fma_f32 v[94:95], v[86:87], v[10:11], v[42:43]
	v_pk_fma_f32 v[96:97], v[84:85], v[12:13], v[40:41]
	v_pk_fma_f32 v[98:99], v[86:87], v[14:15], v[42:43]
	v_cvt_pk_bf16_f32 v106, v88, v89
	v_cvt_pk_bf16_f32 v107, v90, v91
	v_cvt_pk_bf16_f32 v108, v92, v93
	v_cvt_pk_bf16_f32 v109, v94, v95
	v_cvt_pk_bf16_f32 v110, v96, v97
	v_cvt_pk_bf16_f32 v111, v98, v99
	global_store_dwordx2 v2, v[106:107], s[6:7]
	global_store_dwordx2 v2, v[108:109], s[8:9]
	global_store_dwordx2 v2, v[110:111], s[10:11]
	s_add_u32 s6, s6, 0x1000
	s_addc_u32 s7, s7, 0
	s_add_u32 s8, s8, 0x1000
	s_addc_u32 s9, s9, 0
	s_add_u32 s10, s10, 0x1000
	s_addc_u32 s11, s11, 0
	s_waitcnt vmcnt(51)
	v_sub_f32_e32 v84, v40, v44
	v_sub_f32_e32 v85, v41, v45
	v_sub_f32_e32 v86, v42, v46
	v_sub_f32_e32 v87, v43, v47
	v_pk_fma_f32 v[88:89], v[84:85], v[4:5], v[44:45]
	v_pk_fma_f32 v[90:91], v[86:87], v[6:7], v[46:47]
	v_pk_fma_f32 v[92:93], v[84:85], v[8:9], v[44:45]
	v_pk_fma_f32 v[94:95], v[86:87], v[10:11], v[46:47]
	v_pk_fma_f32 v[96:97], v[84:85], v[12:13], v[44:45]
	v_pk_fma_f32 v[98:99], v[86:87], v[14:15], v[46:47]
	v_cvt_pk_bf16_f32 v100, v88, v89
	v_cvt_pk_bf16_f32 v101, v90, v91
	v_cvt_pk_bf16_f32 v102, v92, v93
	v_cvt_pk_bf16_f32 v103, v94, v95
	v_cvt_pk_bf16_f32 v104, v96, v97
	v_cvt_pk_bf16_f32 v105, v98, v99
	global_store_dwordx2 v2, v[100:101], s[6:7]
	global_store_dwordx2 v2, v[102:103], s[8:9]
	global_store_dwordx2 v2, v[104:105], s[10:11]
	s_add_u32 s6, s6, 0x1000
	s_addc_u32 s7, s7, 0
	s_add_u32 s8, s8, 0x1000
	s_addc_u32 s9, s9, 0
	s_add_u32 s10, s10, 0x1000
	s_addc_u32 s11, s11, 0
	s_waitcnt vmcnt(53)
	v_sub_f32_e32 v84, v44, v48
	v_sub_f32_e32 v85, v45, v49
	v_sub_f32_e32 v86, v46, v50
	v_sub_f32_e32 v87, v47, v51
	v_pk_fma_f32 v[88:89], v[84:85], v[4:5], v[48:49]
	v_pk_fma_f32 v[90:91], v[86:87], v[6:7], v[50:51]
	v_pk_fma_f32 v[92:93], v[84:85], v[8:9], v[48:49]
	v_pk_fma_f32 v[94:95], v[86:87], v[10:11], v[50:51]
	v_pk_fma_f32 v[96:97], v[84:85], v[12:13], v[48:49]
	v_pk_fma_f32 v[98:99], v[86:87], v[14:15], v[50:51]
	v_cvt_pk_bf16_f32 v106, v88, v89
	v_cvt_pk_bf16_f32 v107, v90, v91
	v_cvt_pk_bf16_f32 v108, v92, v93
	v_cvt_pk_bf16_f32 v109, v94, v95
	v_cvt_pk_bf16_f32 v110, v96, v97
	v_cvt_pk_bf16_f32 v111, v98, v99
	global_store_dwordx2 v2, v[106:107], s[6:7]
	global_store_dwordx2 v2, v[108:109], s[8:9]
	global_store_dwordx2 v2, v[110:111], s[10:11]
	s_add_u32 s6, s6, 0x1000
	s_addc_u32 s7, s7, 0
	s_add_u32 s8, s8, 0x1000
	s_addc_u32 s9, s9, 0
	s_add_u32 s10, s10, 0x1000
	s_addc_u32 s11, s11, 0
	v_mov_b32_e32 v16, v48
	v_mov_b32_e32 v17, v49
	v_mov_b32_e32 v18, v50
	v_mov_b32_e32 v19, v51
	global_load_dwordx4 v[20:23], v1, s[4:5] nt
	s_add_u32 s4, s4, 0x2000
	s_addc_u32 s5, s5, 0
	global_load_dwordx4 v[24:27], v1, s[4:5] nt
	s_add_u32 s4, s4, 0x2000
	s_addc_u32 s5, s5, 0
	global_load_dwordx4 v[28:31], v1, s[4:5] nt
	s_add_u32 s4, s4, 0x2000
	s_addc_u32 s5, s5, 0
	global_load_dwordx4 v[32:35], v1, s[4:5] nt
	s_add_u32 s4, s4, 0x2000
	s_addc_u32 s5, s5, 0
	global_load_dwordx4 v[36:39], v1, s[4:5] nt
	s_add_u32 s4, s4, 0x2000
	s_addc_u32 s5, s5, 0
	global_load_dwordx4 v[40:43], v1, s[4:5] nt
	s_add_u32 s4, s4, 0x2000
	s_addc_u32 s5, s5, 0
	global_load_dwordx4 v[44:47], v1, s[4:5] nt
	s_add_u32 s4, s4, 0x2000
	s_addc_u32 s5, s5, 0
	global_load_dwordx4 v[48:51], v1, s[4:5] nt
	s_add_u32 s4, s4, 0x2000
	s_addc_u32 s5, s5, 0
	s_waitcnt vmcnt(39)
	v_sub_f32_e32 v84, v16, v52
	v_sub_f32_e32 v85, v17, v53
	v_sub_f32_e32 v86, v18, v54
	v_sub_f32_e32 v87, v19, v55
	v_pk_fma_f32 v[88:89], v[84:85], v[4:5], v[52:53]
	v_pk_fma_f32 v[90:91], v[86:87], v[6:7], v[54:55]
	v_pk_fma_f32 v[92:93], v[84:85], v[8:9], v[52:53]
	v_pk_fma_f32 v[94:95], v[86:87], v[10:11], v[54:55]
	v_pk_fma_f32 v[96:97], v[84:85], v[12:13], v[52:53]
	v_pk_fma_f32 v[98:99], v[86:87], v[14:15], v[54:55]
	v_cvt_pk_bf16_f32 v100, v88, v89
	v_cvt_pk_bf16_f32 v101, v90, v91
	v_cvt_pk_bf16_f32 v102, v92, v93
	v_cvt_pk_bf16_f32 v103, v94, v95
	v_cvt_pk_bf16_f32 v104, v96, v97
	v_cvt_pk_bf16_f32 v105, v98, v99
	global_store_dwordx2 v2, v[100:101], s[6:7]
	global_store_dwordx2 v2, v[102:103], s[8:9]
	global_store_dwordx2 v2, v[104:105], s[10:11]
	s_add_u32 s6, s6, 0x1000
	s_addc_u32 s7, s7, 0
	s_add_u32 s8, s8, 0x1000
	s_addc_u32 s9, s9, 0
	s_add_u32 s10, s10, 0x1000
	s_addc_u32 s11, s11, 0
	s_waitcnt vmcnt(41)
	v_sub_f32_e32 v84, v52, v56
	v_sub_f32_e32 v85, v53, v57
	v_sub_f32_e32 v86, v54, v58
	v_sub_f32_e32 v87, v55, v59
	v_pk_fma_f32 v[88:89], v[84:85], v[4:5], v[56:57]
	v_pk_fma_f32 v[90:91], v[86:87], v[6:7], v[58:59]
	v_pk_fma_f32 v[92:93], v[84:85], v[8:9], v[56:57]
	v_pk_fma_f32 v[94:95], v[86:87], v[10:11], v[58:59]
	v_pk_fma_f32 v[96:97], v[84:85], v[12:13], v[56:57]
	v_pk_fma_f32 v[98:99], v[86:87], v[14:15], v[58:59]
	v_cvt_pk_bf16_f32 v106, v88, v89
	v_cvt_pk_bf16_f32 v107, v90, v91
	v_cvt_pk_bf16_f32 v108, v92, v93
	v_cvt_pk_bf16_f32 v109, v94, v95
	v_cvt_pk_bf16_f32 v110, v96, v97
	v_cvt_pk_bf16_f32 v111, v98, v99
	global_store_dwordx2 v2, v[106:107], s[6:7]
	global_store_dwordx2 v2, v[108:109], s[8:9]
	global_store_dwordx2 v2, v[110:111], s[10:11]
	s_add_u32 s6, s6, 0x1000
	s_addc_u32 s7, s7, 0
	s_add_u32 s8, s8, 0x1000
	s_addc_u32 s9, s9, 0
	s_add_u32 s10, s10, 0x1000
	s_addc_u32 s11, s11, 0
	s_waitcnt vmcnt(43)
	v_sub_f32_e32 v84, v56, v60
	v_sub_f32_e32 v85, v57, v61
	v_sub_f32_e32 v86, v58, v62
	v_sub_f32_e32 v87, v59, v63
	v_pk_fma_f32 v[88:89], v[84:85], v[4:5], v[60:61]
	v_pk_fma_f32 v[90:91], v[86:87], v[6:7], v[62:63]
	v_pk_fma_f32 v[92:93], v[84:85], v[8:9], v[60:61]
	v_pk_fma_f32 v[94:95], v[86:87], v[10:11], v[62:63]
	v_pk_fma_f32 v[96:97], v[84:85], v[12:13], v[60:61]
	v_pk_fma_f32 v[98:99], v[86:87], v[14:15], v[62:63]
	v_cvt_pk_bf16_f32 v100, v88, v89
	v_cvt_pk_bf16_f32 v101, v90, v91
	v_cvt_pk_bf16_f32 v102, v92, v93
	v_cvt_pk_bf16_f32 v103, v94, v95
	v_cvt_pk_bf16_f32 v104, v96, v97
	v_cvt_pk_bf16_f32 v105, v98, v99
	global_store_dwordx2 v2, v[100:101], s[6:7]
	global_store_dwordx2 v2, v[102:103], s[8:9]
	global_store_dwordx2 v2, v[104:105], s[10:11]
	s_add_u32 s6, s6, 0x1000
	s_addc_u32 s7, s7, 0
	s_add_u32 s8, s8, 0x1000
	s_addc_u32 s9, s9, 0
	s_add_u32 s10, s10, 0x1000
	s_addc_u32 s11, s11, 0
	s_waitcnt vmcnt(45)
	v_sub_f32_e32 v84, v60, v64
	v_sub_f32_e32 v85, v61, v65
	v_sub_f32_e32 v86, v62, v66
	v_sub_f32_e32 v87, v63, v67
	v_pk_fma_f32 v[88:89], v[84:85], v[4:5], v[64:65]
	v_pk_fma_f32 v[90:91], v[86:87], v[6:7], v[66:67]
	v_pk_fma_f32 v[92:93], v[84:85], v[8:9], v[64:65]
	v_pk_fma_f32 v[94:95], v[86:87], v[10:11], v[66:67]
	v_pk_fma_f32 v[96:97], v[84:85], v[12:13], v[64:65]
	v_pk_fma_f32 v[98:99], v[86:87], v[14:15], v[66:67]
	v_cvt_pk_bf16_f32 v106, v88, v89
	v_cvt_pk_bf16_f32 v107, v90, v91
	v_cvt_pk_bf16_f32 v108, v92, v93
	v_cvt_pk_bf16_f32 v109, v94, v95
	v_cvt_pk_bf16_f32 v110, v96, v97
	v_cvt_pk_bf16_f32 v111, v98, v99
	global_store_dwordx2 v2, v[106:107], s[6:7]
	global_store_dwordx2 v2, v[108:109], s[8:9]
	global_store_dwordx2 v2, v[110:111], s[10:11]
	s_add_u32 s6, s6, 0x1000
	s_addc_u32 s7, s7, 0
	s_add_u32 s8, s8, 0x1000
	s_addc_u32 s9, s9, 0
	s_add_u32 s10, s10, 0x1000
	s_addc_u32 s11, s11, 0
	s_waitcnt vmcnt(47)
	v_sub_f32_e32 v84, v64, v68
	v_sub_f32_e32 v85, v65, v69
	v_sub_f32_e32 v86, v66, v70
	v_sub_f32_e32 v87, v67, v71
	v_pk_fma_f32 v[88:89], v[84:85], v[4:5], v[68:69]
	v_pk_fma_f32 v[90:91], v[86:87], v[6:7], v[70:71]
	v_pk_fma_f32 v[92:93], v[84:85], v[8:9], v[68:69]
	v_pk_fma_f32 v[94:95], v[86:87], v[10:11], v[70:71]
	v_pk_fma_f32 v[96:97], v[84:85], v[12:13], v[68:69]
	v_pk_fma_f32 v[98:99], v[86:87], v[14:15], v[70:71]
	v_cvt_pk_bf16_f32 v100, v88, v89
	v_cvt_pk_bf16_f32 v101, v90, v91
	v_cvt_pk_bf16_f32 v102, v92, v93
	v_cvt_pk_bf16_f32 v103, v94, v95
	v_cvt_pk_bf16_f32 v104, v96, v97
	v_cvt_pk_bf16_f32 v105, v98, v99
	global_store_dwordx2 v2, v[100:101], s[6:7]
	global_store_dwordx2 v2, v[102:103], s[8:9]
	global_store_dwordx2 v2, v[104:105], s[10:11]
	s_add_u32 s6, s6, 0x1000
	s_addc_u32 s7, s7, 0
	s_add_u32 s8, s8, 0x1000
	s_addc_u32 s9, s9, 0
	s_add_u32 s10, s10, 0x1000
	s_addc_u32 s11, s11, 0
	s_waitcnt vmcnt(49)
	v_sub_f32_e32 v84, v68, v72
	v_sub_f32_e32 v85, v69, v73
	v_sub_f32_e32 v86, v70, v74
	v_sub_f32_e32 v87, v71, v75
	v_pk_fma_f32 v[88:89], v[84:85], v[4:5], v[72:73]
	v_pk_fma_f32 v[90:91], v[86:87], v[6:7], v[74:75]
	v_pk_fma_f32 v[92:93], v[84:85], v[8:9], v[72:73]
	v_pk_fma_f32 v[94:95], v[86:87], v[10:11], v[74:75]
	v_pk_fma_f32 v[96:97], v[84:85], v[12:13], v[72:73]
	v_pk_fma_f32 v[98:99], v[86:87], v[14:15], v[74:75]
	v_cvt_pk_bf16_f32 v106, v88, v89
	v_cvt_pk_bf16_f32 v107, v90, v91
	v_cvt_pk_bf16_f32 v108, v92, v93
	v_cvt_pk_bf16_f32 v109, v94, v95
	v_cvt_pk_bf16_f32 v110, v96, v97
	v_cvt_pk_bf16_f32 v111, v98, v99
	global_store_dwordx2 v2, v[106:107], s[6:7]
	global_store_dwordx2 v2, v[108:109], s[8:9]
	global_store_dwordx2 v2, v[110:111], s[10:11]
	s_add_u32 s6, s6, 0x1000
	s_addc_u32 s7, s7, 0
	s_add_u32 s8, s8, 0x1000
	s_addc_u32 s9, s9, 0
	s_add_u32 s10, s10, 0x1000
	s_addc_u32 s11, s11, 0
	s_waitcnt vmcnt(51)
	v_sub_f32_e32 v84, v72, v76
	v_sub_f32_e32 v85, v73, v77
	v_sub_f32_e32 v86, v74, v78
	v_sub_f32_e32 v87, v75, v79
	v_pk_fma_f32 v[88:89], v[84:85], v[4:5], v[76:77]
	v_pk_fma_f32 v[90:91], v[86:87], v[6:7], v[78:79]
	v_pk_fma_f32 v[92:93], v[84:85], v[8:9], v[76:77]
	v_pk_fma_f32 v[94:95], v[86:87], v[10:11], v[78:79]
	v_pk_fma_f32 v[96:97], v[84:85], v[12:13], v[76:77]
	v_pk_fma_f32 v[98:99], v[86:87], v[14:15], v[78:79]
	v_cvt_pk_bf16_f32 v100, v88, v89
	v_cvt_pk_bf16_f32 v101, v90, v91
	v_cvt_pk_bf16_f32 v102, v92, v93
	v_cvt_pk_bf16_f32 v103, v94, v95
	v_cvt_pk_bf16_f32 v104, v96, v97
	v_cvt_pk_bf16_f32 v105, v98, v99
	global_store_dwordx2 v2, v[100:101], s[6:7]
	global_store_dwordx2 v2, v[102:103], s[8:9]
	global_store_dwordx2 v2, v[104:105], s[10:11]
	s_add_u32 s6, s6, 0x1000
	s_addc_u32 s7, s7, 0
	s_add_u32 s8, s8, 0x1000
	s_addc_u32 s9, s9, 0
	s_add_u32 s10, s10, 0x1000
	s_addc_u32 s11, s11, 0
	s_waitcnt vmcnt(53)
	v_sub_f32_e32 v84, v76, v80
	v_sub_f32_e32 v85, v77, v81
	v_sub_f32_e32 v86, v78, v82
	v_sub_f32_e32 v87, v79, v83
	v_pk_fma_f32 v[88:89], v[84:85], v[4:5], v[80:81]
	v_pk_fma_f32 v[90:91], v[86:87], v[6:7], v[82:83]
	v_pk_fma_f32 v[92:93], v[84:85], v[8:9], v[80:81]
	v_pk_fma_f32 v[94:95], v[86:87], v[10:11], v[82:83]
	v_pk_fma_f32 v[96:97], v[84:85], v[12:13], v[80:81]
	v_pk_fma_f32 v[98:99], v[86:87], v[14:15], v[82:83]
	v_cvt_pk_bf16_f32 v106, v88, v89
	v_cvt_pk_bf16_f32 v107, v90, v91
	v_cvt_pk_bf16_f32 v108, v92, v93
	v_cvt_pk_bf16_f32 v109, v94, v95
	v_cvt_pk_bf16_f32 v110, v96, v97
	v_cvt_pk_bf16_f32 v111, v98, v99
	global_store_dwordx2 v2, v[106:107], s[6:7]
	global_store_dwordx2 v2, v[108:109], s[8:9]
	global_store_dwordx2 v2, v[110:111], s[10:11]
	s_add_u32 s6, s6, 0x1000
	s_addc_u32 s7, s7, 0
	s_add_u32 s8, s8, 0x1000
	s_addc_u32 s9, s9, 0
	s_add_u32 s10, s10, 0x1000
	s_addc_u32 s11, s11, 0
	v_mov_b32_e32 v16, v80
	v_mov_b32_e32 v17, v81
	v_mov_b32_e32 v18, v82
	v_mov_b32_e32 v19, v83
	global_load_dwordx4 v[52:55], v1, s[4:5] nt
	s_add_u32 s4, s4, 0x2000
	s_addc_u32 s5, s5, 0
	global_load_dwordx4 v[56:59], v1, s[4:5] nt
	s_add_u32 s4, s4, 0x2000
	s_addc_u32 s5, s5, 0
	global_load_dwordx4 v[60:63], v1, s[4:5] nt
	s_add_u32 s4, s4, 0x2000
	s_addc_u32 s5, s5, 0
	global_load_dwordx4 v[64:67], v1, s[4:5] nt
	s_add_u32 s4, s4, 0x2000
	s_addc_u32 s5, s5, 0
	global_load_dwordx4 v[68:71], v1, s[4:5] nt
	s_add_u32 s4, s4, 0x2000
	s_addc_u32 s5, s5, 0
	global_load_dwordx4 v[72:75], v1, s[4:5] nt
	s_add_u32 s4, s4, 0x2000
	s_addc_u32 s5, s5, 0
	global_load_dwordx4 v[76:79], v1, s[4:5] nt
	s_add_u32 s4, s4, 0x2000
	s_addc_u32 s5, s5, 0
	global_load_dwordx4 v[80:83], v1, s[4:5] nt
	s_add_u32 s4, s4, 0x2000
	s_addc_u32 s5, s5, 0
	s_waitcnt vmcnt(39)
	v_sub_f32_e32 v84, v16, v20
	v_sub_f32_e32 v85, v17, v21
	v_sub_f32_e32 v86, v18, v22
	v_sub_f32_e32 v87, v19, v23
	v_pk_fma_f32 v[88:89], v[84:85], v[4:5], v[20:21]
	v_pk_fma_f32 v[90:91], v[86:87], v[6:7], v[22:23]
	v_pk_fma_f32 v[92:93], v[84:85], v[8:9], v[20:21]
	v_pk_fma_f32 v[94:95], v[86:87], v[10:11], v[22:23]
	v_pk_fma_f32 v[96:97], v[84:85], v[12:13], v[20:21]
	v_pk_fma_f32 v[98:99], v[86:87], v[14:15], v[22:23]
	v_cvt_pk_bf16_f32 v100, v88, v89
	v_cvt_pk_bf16_f32 v101, v90, v91
	v_cvt_pk_bf16_f32 v102, v92, v93
	v_cvt_pk_bf16_f32 v103, v94, v95
	v_cvt_pk_bf16_f32 v104, v96, v97
	v_cvt_pk_bf16_f32 v105, v98, v99
	global_store_dwordx2 v2, v[100:101], s[6:7]
	global_store_dwordx2 v2, v[102:103], s[8:9]
	global_store_dwordx2 v2, v[104:105], s[10:11]
	s_add_u32 s6, s6, 0x1000
	s_addc_u32 s7, s7, 0
	s_add_u32 s8, s8, 0x1000
	s_addc_u32 s9, s9, 0
	s_add_u32 s10, s10, 0x1000
	s_addc_u32 s11, s11, 0
	s_waitcnt vmcnt(41)
	v_sub_f32_e32 v84, v20, v24
	v_sub_f32_e32 v85, v21, v25
	v_sub_f32_e32 v86, v22, v26
	v_sub_f32_e32 v87, v23, v27
	v_pk_fma_f32 v[88:89], v[84:85], v[4:5], v[24:25]
	v_pk_fma_f32 v[90:91], v[86:87], v[6:7], v[26:27]
	v_pk_fma_f32 v[92:93], v[84:85], v[8:9], v[24:25]
	v_pk_fma_f32 v[94:95], v[86:87], v[10:11], v[26:27]
	v_pk_fma_f32 v[96:97], v[84:85], v[12:13], v[24:25]
	v_pk_fma_f32 v[98:99], v[86:87], v[14:15], v[26:27]
	v_cvt_pk_bf16_f32 v106, v88, v89
	v_cvt_pk_bf16_f32 v107, v90, v91
	v_cvt_pk_bf16_f32 v108, v92, v93
	v_cvt_pk_bf16_f32 v109, v94, v95
	v_cvt_pk_bf16_f32 v110, v96, v97
	v_cvt_pk_bf16_f32 v111, v98, v99
	global_store_dwordx2 v2, v[106:107], s[6:7]
	global_store_dwordx2 v2, v[108:109], s[8:9]
	global_store_dwordx2 v2, v[110:111], s[10:11]
	s_add_u32 s6, s6, 0x1000
	s_addc_u32 s7, s7, 0
	s_add_u32 s8, s8, 0x1000
	s_addc_u32 s9, s9, 0
	s_add_u32 s10, s10, 0x1000
	s_addc_u32 s11, s11, 0
	s_waitcnt vmcnt(43)
	v_sub_f32_e32 v84, v24, v28
	v_sub_f32_e32 v85, v25, v29
	v_sub_f32_e32 v86, v26, v30
	v_sub_f32_e32 v87, v27, v31
	v_pk_fma_f32 v[88:89], v[84:85], v[4:5], v[28:29]
	v_pk_fma_f32 v[90:91], v[86:87], v[6:7], v[30:31]
	v_pk_fma_f32 v[92:93], v[84:85], v[8:9], v[28:29]
	v_pk_fma_f32 v[94:95], v[86:87], v[10:11], v[30:31]
	v_pk_fma_f32 v[96:97], v[84:85], v[12:13], v[28:29]
	v_pk_fma_f32 v[98:99], v[86:87], v[14:15], v[30:31]
	v_cvt_pk_bf16_f32 v100, v88, v89
	v_cvt_pk_bf16_f32 v101, v90, v91
	v_cvt_pk_bf16_f32 v102, v92, v93
	v_cvt_pk_bf16_f32 v103, v94, v95
	v_cvt_pk_bf16_f32 v104, v96, v97
	v_cvt_pk_bf16_f32 v105, v98, v99
	global_store_dwordx2 v2, v[100:101], s[6:7]
	global_store_dwordx2 v2, v[102:103], s[8:9]
	global_store_dwordx2 v2, v[104:105], s[10:11]
	s_add_u32 s6, s6, 0x1000
	s_addc_u32 s7, s7, 0
	s_add_u32 s8, s8, 0x1000
	s_addc_u32 s9, s9, 0
	s_add_u32 s10, s10, 0x1000
	s_addc_u32 s11, s11, 0
	s_waitcnt vmcnt(45)
	v_sub_f32_e32 v84, v28, v32
	v_sub_f32_e32 v85, v29, v33
	v_sub_f32_e32 v86, v30, v34
	v_sub_f32_e32 v87, v31, v35
	v_pk_fma_f32 v[88:89], v[84:85], v[4:5], v[32:33]
	v_pk_fma_f32 v[90:91], v[86:87], v[6:7], v[34:35]
	v_pk_fma_f32 v[92:93], v[84:85], v[8:9], v[32:33]
	v_pk_fma_f32 v[94:95], v[86:87], v[10:11], v[34:35]
	v_pk_fma_f32 v[96:97], v[84:85], v[12:13], v[32:33]
	v_pk_fma_f32 v[98:99], v[86:87], v[14:15], v[34:35]
	v_cvt_pk_bf16_f32 v106, v88, v89
	v_cvt_pk_bf16_f32 v107, v90, v91
	v_cvt_pk_bf16_f32 v108, v92, v93
	v_cvt_pk_bf16_f32 v109, v94, v95
	v_cvt_pk_bf16_f32 v110, v96, v97
	v_cvt_pk_bf16_f32 v111, v98, v99
	global_store_dwordx2 v2, v[106:107], s[6:7]
	global_store_dwordx2 v2, v[108:109], s[8:9]
	global_store_dwordx2 v2, v[110:111], s[10:11]
	s_add_u32 s6, s6, 0x1000
	s_addc_u32 s7, s7, 0
	s_add_u32 s8, s8, 0x1000
	s_addc_u32 s9, s9, 0
	s_add_u32 s10, s10, 0x1000
	s_addc_u32 s11, s11, 0
	s_waitcnt vmcnt(47)
	v_sub_f32_e32 v84, v32, v36
	v_sub_f32_e32 v85, v33, v37
	v_sub_f32_e32 v86, v34, v38
	v_sub_f32_e32 v87, v35, v39
	v_pk_fma_f32 v[88:89], v[84:85], v[4:5], v[36:37]
	v_pk_fma_f32 v[90:91], v[86:87], v[6:7], v[38:39]
	v_pk_fma_f32 v[92:93], v[84:85], v[8:9], v[36:37]
	v_pk_fma_f32 v[94:95], v[86:87], v[10:11], v[38:39]
	v_pk_fma_f32 v[96:97], v[84:85], v[12:13], v[36:37]
	v_pk_fma_f32 v[98:99], v[86:87], v[14:15], v[38:39]
	v_cvt_pk_bf16_f32 v100, v88, v89
	v_cvt_pk_bf16_f32 v101, v90, v91
	v_cvt_pk_bf16_f32 v102, v92, v93
	v_cvt_pk_bf16_f32 v103, v94, v95
	v_cvt_pk_bf16_f32 v104, v96, v97
	v_cvt_pk_bf16_f32 v105, v98, v99
	global_store_dwordx2 v2, v[100:101], s[6:7]
	global_store_dwordx2 v2, v[102:103], s[8:9]
	global_store_dwordx2 v2, v[104:105], s[10:11]
	s_add_u32 s6, s6, 0x1000
	s_addc_u32 s7, s7, 0
	s_add_u32 s8, s8, 0x1000
	s_addc_u32 s9, s9, 0
	s_add_u32 s10, s10, 0x1000
	s_addc_u32 s11, s11, 0
	s_waitcnt vmcnt(49)
	v_sub_f32_e32 v84, v36, v40
	v_sub_f32_e32 v85, v37, v41
	v_sub_f32_e32 v86, v38, v42
	v_sub_f32_e32 v87, v39, v43
	v_pk_fma_f32 v[88:89], v[84:85], v[4:5], v[40:41]
	v_pk_fma_f32 v[90:91], v[86:87], v[6:7], v[42:43]
	v_pk_fma_f32 v[92:93], v[84:85], v[8:9], v[40:41]
	v_pk_fma_f32 v[94:95], v[86:87], v[10:11], v[42:43]
	v_pk_fma_f32 v[96:97], v[84:85], v[12:13], v[40:41]
	v_pk_fma_f32 v[98:99], v[86:87], v[14:15], v[42:43]
	v_cvt_pk_bf16_f32 v106, v88, v89
	v_cvt_pk_bf16_f32 v107, v90, v91
	v_cvt_pk_bf16_f32 v108, v92, v93
	v_cvt_pk_bf16_f32 v109, v94, v95
	v_cvt_pk_bf16_f32 v110, v96, v97
	v_cvt_pk_bf16_f32 v111, v98, v99
	global_store_dwordx2 v2, v[106:107], s[6:7]
	global_store_dwordx2 v2, v[108:109], s[8:9]
	global_store_dwordx2 v2, v[110:111], s[10:11]
	s_add_u32 s6, s6, 0x1000
	s_addc_u32 s7, s7, 0
	s_add_u32 s8, s8, 0x1000
	s_addc_u32 s9, s9, 0
	s_add_u32 s10, s10, 0x1000
	s_addc_u32 s11, s11, 0
	s_waitcnt vmcnt(51)
	v_sub_f32_e32 v84, v40, v44
	v_sub_f32_e32 v85, v41, v45
	v_sub_f32_e32 v86, v42, v46
	v_sub_f32_e32 v87, v43, v47
	v_pk_fma_f32 v[88:89], v[84:85], v[4:5], v[44:45]
	v_pk_fma_f32 v[90:91], v[86:87], v[6:7], v[46:47]
	v_pk_fma_f32 v[92:93], v[84:85], v[8:9], v[44:45]
	v_pk_fma_f32 v[94:95], v[86:87], v[10:11], v[46:47]
	v_pk_fma_f32 v[96:97], v[84:85], v[12:13], v[44:45]
	v_pk_fma_f32 v[98:99], v[86:87], v[14:15], v[46:47]
	v_cvt_pk_bf16_f32 v100, v88, v89
	v_cvt_pk_bf16_f32 v101, v90, v91
	v_cvt_pk_bf16_f32 v102, v92, v93
	v_cvt_pk_bf16_f32 v103, v94, v95
	v_cvt_pk_bf16_f32 v104, v96, v97
	v_cvt_pk_bf16_f32 v105, v98, v99
	global_store_dwordx2 v2, v[100:101], s[6:7]
	global_store_dwordx2 v2, v[102:103], s[8:9]
	global_store_dwordx2 v2, v[104:105], s[10:11]
	s_add_u32 s6, s6, 0x1000
	s_addc_u32 s7, s7, 0
	s_add_u32 s8, s8, 0x1000
	s_addc_u32 s9, s9, 0
	s_add_u32 s10, s10, 0x1000
	s_addc_u32 s11, s11, 0
	s_waitcnt vmcnt(53)
	v_sub_f32_e32 v84, v44, v48
	v_sub_f32_e32 v85, v45, v49
	v_sub_f32_e32 v86, v46, v50
	v_sub_f32_e32 v87, v47, v51
	v_pk_fma_f32 v[88:89], v[84:85], v[4:5], v[48:49]
	v_pk_fma_f32 v[90:91], v[86:87], v[6:7], v[50:51]
	v_pk_fma_f32 v[92:93], v[84:85], v[8:9], v[48:49]
	v_pk_fma_f32 v[94:95], v[86:87], v[10:11], v[50:51]
	v_pk_fma_f32 v[96:97], v[84:85], v[12:13], v[48:49]
	v_pk_fma_f32 v[98:99], v[86:87], v[14:15], v[50:51]
	v_cvt_pk_bf16_f32 v106, v88, v89
	v_cvt_pk_bf16_f32 v107, v90, v91
	v_cvt_pk_bf16_f32 v108, v92, v93
	v_cvt_pk_bf16_f32 v109, v94, v95
	v_cvt_pk_bf16_f32 v110, v96, v97
	v_cvt_pk_bf16_f32 v111, v98, v99
	global_store_dwordx2 v2, v[106:107], s[6:7]
	global_store_dwordx2 v2, v[108:109], s[8:9]
	global_store_dwordx2 v2, v[110:111], s[10:11]
	s_add_u32 s6, s6, 0x1000
	s_addc_u32 s7, s7, 0
	s_add_u32 s8, s8, 0x1000
	s_addc_u32 s9, s9, 0
	s_add_u32 s10, s10, 0x1000
	s_addc_u32 s11, s11, 0
	v_mov_b32_e32 v16, v48
	v_mov_b32_e32 v17, v49
	v_mov_b32_e32 v18, v50
	v_mov_b32_e32 v19, v51
	s_waitcnt vmcnt(31)
	v_sub_f32_e32 v84, v16, v52
	v_sub_f32_e32 v85, v17, v53
	v_sub_f32_e32 v86, v18, v54
	v_sub_f32_e32 v87, v19, v55
	v_pk_fma_f32 v[88:89], v[84:85], v[4:5], v[52:53]
	v_pk_fma_f32 v[90:91], v[86:87], v[6:7], v[54:55]
	v_pk_fma_f32 v[92:93], v[84:85], v[8:9], v[52:53]
	v_pk_fma_f32 v[94:95], v[86:87], v[10:11], v[54:55]
	v_pk_fma_f32 v[96:97], v[84:85], v[12:13], v[52:53]
	v_pk_fma_f32 v[98:99], v[86:87], v[14:15], v[54:55]
	v_cvt_pk_bf16_f32 v100, v88, v89
	v_cvt_pk_bf16_f32 v101, v90, v91
	v_cvt_pk_bf16_f32 v102, v92, v93
	v_cvt_pk_bf16_f32 v103, v94, v95
	v_cvt_pk_bf16_f32 v104, v96, v97
	v_cvt_pk_bf16_f32 v105, v98, v99
	global_store_dwordx2 v2, v[100:101], s[6:7]
	global_store_dwordx2 v2, v[102:103], s[8:9]
	global_store_dwordx2 v2, v[104:105], s[10:11]
	s_add_u32 s6, s6, 0x1000
	s_addc_u32 s7, s7, 0
	s_add_u32 s8, s8, 0x1000
	s_addc_u32 s9, s9, 0
	s_add_u32 s10, s10, 0x1000
	s_addc_u32 s11, s11, 0
	s_waitcnt vmcnt(33)
	v_sub_f32_e32 v84, v52, v56
	v_sub_f32_e32 v85, v53, v57
	v_sub_f32_e32 v86, v54, v58
	v_sub_f32_e32 v87, v55, v59
	v_pk_fma_f32 v[88:89], v[84:85], v[4:5], v[56:57]
	v_pk_fma_f32 v[90:91], v[86:87], v[6:7], v[58:59]
	v_pk_fma_f32 v[92:93], v[84:85], v[8:9], v[56:57]
	v_pk_fma_f32 v[94:95], v[86:87], v[10:11], v[58:59]
	v_pk_fma_f32 v[96:97], v[84:85], v[12:13], v[56:57]
	v_pk_fma_f32 v[98:99], v[86:87], v[14:15], v[58:59]
	v_cvt_pk_bf16_f32 v106, v88, v89
	v_cvt_pk_bf16_f32 v107, v90, v91
	v_cvt_pk_bf16_f32 v108, v92, v93
	v_cvt_pk_bf16_f32 v109, v94, v95
	v_cvt_pk_bf16_f32 v110, v96, v97
	v_cvt_pk_bf16_f32 v111, v98, v99
	global_store_dwordx2 v2, v[106:107], s[6:7]
	global_store_dwordx2 v2, v[108:109], s[8:9]
	global_store_dwordx2 v2, v[110:111], s[10:11]
	s_add_u32 s6, s6, 0x1000
	s_addc_u32 s7, s7, 0
	s_add_u32 s8, s8, 0x1000
	s_addc_u32 s9, s9, 0
	s_add_u32 s10, s10, 0x1000
	s_addc_u32 s11, s11, 0
	s_waitcnt vmcnt(35)
	v_sub_f32_e32 v84, v56, v60
	v_sub_f32_e32 v85, v57, v61
	v_sub_f32_e32 v86, v58, v62
	v_sub_f32_e32 v87, v59, v63
	v_pk_fma_f32 v[88:89], v[84:85], v[4:5], v[60:61]
	v_pk_fma_f32 v[90:91], v[86:87], v[6:7], v[62:63]
	v_pk_fma_f32 v[92:93], v[84:85], v[8:9], v[60:61]
	v_pk_fma_f32 v[94:95], v[86:87], v[10:11], v[62:63]
	v_pk_fma_f32 v[96:97], v[84:85], v[12:13], v[60:61]
	v_pk_fma_f32 v[98:99], v[86:87], v[14:15], v[62:63]
	v_cvt_pk_bf16_f32 v100, v88, v89
	v_cvt_pk_bf16_f32 v101, v90, v91
	v_cvt_pk_bf16_f32 v102, v92, v93
	v_cvt_pk_bf16_f32 v103, v94, v95
	v_cvt_pk_bf16_f32 v104, v96, v97
	v_cvt_pk_bf16_f32 v105, v98, v99
	global_store_dwordx2 v2, v[100:101], s[6:7]
	global_store_dwordx2 v2, v[102:103], s[8:9]
	global_store_dwordx2 v2, v[104:105], s[10:11]
	s_add_u32 s6, s6, 0x1000
	s_addc_u32 s7, s7, 0
	s_add_u32 s8, s8, 0x1000
	s_addc_u32 s9, s9, 0
	s_add_u32 s10, s10, 0x1000
	s_addc_u32 s11, s11, 0
	s_waitcnt vmcnt(37)
	v_sub_f32_e32 v84, v60, v64
	v_sub_f32_e32 v85, v61, v65
	v_sub_f32_e32 v86, v62, v66
	v_sub_f32_e32 v87, v63, v67
	v_pk_fma_f32 v[88:89], v[84:85], v[4:5], v[64:65]
	v_pk_fma_f32 v[90:91], v[86:87], v[6:7], v[66:67]
	v_pk_fma_f32 v[92:93], v[84:85], v[8:9], v[64:65]
	v_pk_fma_f32 v[94:95], v[86:87], v[10:11], v[66:67]
	v_pk_fma_f32 v[96:97], v[84:85], v[12:13], v[64:65]
	v_pk_fma_f32 v[98:99], v[86:87], v[14:15], v[66:67]
	v_cvt_pk_bf16_f32 v106, v88, v89
	v_cvt_pk_bf16_f32 v107, v90, v91
	v_cvt_pk_bf16_f32 v108, v92, v93
	v_cvt_pk_bf16_f32 v109, v94, v95
	v_cvt_pk_bf16_f32 v110, v96, v97
	v_cvt_pk_bf16_f32 v111, v98, v99
	global_store_dwordx2 v2, v[106:107], s[6:7]
	global_store_dwordx2 v2, v[108:109], s[8:9]
	global_store_dwordx2 v2, v[110:111], s[10:11]
	s_add_u32 s6, s6, 0x1000
	s_addc_u32 s7, s7, 0
	s_add_u32 s8, s8, 0x1000
	s_addc_u32 s9, s9, 0
	s_add_u32 s10, s10, 0x1000
	s_addc_u32 s11, s11, 0
	s_waitcnt vmcnt(39)
	v_sub_f32_e32 v84, v64, v68
	v_sub_f32_e32 v85, v65, v69
	v_sub_f32_e32 v86, v66, v70
	v_sub_f32_e32 v87, v67, v71
	v_pk_fma_f32 v[88:89], v[84:85], v[4:5], v[68:69]
	v_pk_fma_f32 v[90:91], v[86:87], v[6:7], v[70:71]
	v_pk_fma_f32 v[92:93], v[84:85], v[8:9], v[68:69]
	v_pk_fma_f32 v[94:95], v[86:87], v[10:11], v[70:71]
	v_pk_fma_f32 v[96:97], v[84:85], v[12:13], v[68:69]
	v_pk_fma_f32 v[98:99], v[86:87], v[14:15], v[70:71]
	v_cvt_pk_bf16_f32 v100, v88, v89
	v_cvt_pk_bf16_f32 v101, v90, v91
	v_cvt_pk_bf16_f32 v102, v92, v93
	v_cvt_pk_bf16_f32 v103, v94, v95
	v_cvt_pk_bf16_f32 v104, v96, v97
	v_cvt_pk_bf16_f32 v105, v98, v99
	global_store_dwordx2 v2, v[100:101], s[6:7]
	global_store_dwordx2 v2, v[102:103], s[8:9]
	global_store_dwordx2 v2, v[104:105], s[10:11]
	s_add_u32 s6, s6, 0x1000
	s_addc_u32 s7, s7, 0
	s_add_u32 s8, s8, 0x1000
	s_addc_u32 s9, s9, 0
	s_add_u32 s10, s10, 0x1000
	s_addc_u32 s11, s11, 0
	s_waitcnt vmcnt(41)
	v_sub_f32_e32 v84, v68, v72
	v_sub_f32_e32 v85, v69, v73
	v_sub_f32_e32 v86, v70, v74
	v_sub_f32_e32 v87, v71, v75
	v_pk_fma_f32 v[88:89], v[84:85], v[4:5], v[72:73]
	v_pk_fma_f32 v[90:91], v[86:87], v[6:7], v[74:75]
	v_pk_fma_f32 v[92:93], v[84:85], v[8:9], v[72:73]
	v_pk_fma_f32 v[94:95], v[86:87], v[10:11], v[74:75]
	v_pk_fma_f32 v[96:97], v[84:85], v[12:13], v[72:73]
	v_pk_fma_f32 v[98:99], v[86:87], v[14:15], v[74:75]
	v_cvt_pk_bf16_f32 v106, v88, v89
	v_cvt_pk_bf16_f32 v107, v90, v91
	v_cvt_pk_bf16_f32 v108, v92, v93
	v_cvt_pk_bf16_f32 v109, v94, v95
	v_cvt_pk_bf16_f32 v110, v96, v97
	v_cvt_pk_bf16_f32 v111, v98, v99
	global_store_dwordx2 v2, v[106:107], s[6:7]
	global_store_dwordx2 v2, v[108:109], s[8:9]
	global_store_dwordx2 v2, v[110:111], s[10:11]
	s_add_u32 s6, s6, 0x1000
	s_addc_u32 s7, s7, 0
	s_add_u32 s8, s8, 0x1000
	s_addc_u32 s9, s9, 0
	s_add_u32 s10, s10, 0x1000
	s_addc_u32 s11, s11, 0
	s_waitcnt vmcnt(43)
	v_sub_f32_e32 v84, v72, v76
	v_sub_f32_e32 v85, v73, v77
	v_sub_f32_e32 v86, v74, v78
	v_sub_f32_e32 v87, v75, v79
	v_pk_fma_f32 v[88:89], v[84:85], v[4:5], v[76:77]
	v_pk_fma_f32 v[90:91], v[86:87], v[6:7], v[78:79]
	v_pk_fma_f32 v[92:93], v[84:85], v[8:9], v[76:77]
	v_pk_fma_f32 v[94:95], v[86:87], v[10:11], v[78:79]
	v_pk_fma_f32 v[96:97], v[84:85], v[12:13], v[76:77]
	v_pk_fma_f32 v[98:99], v[86:87], v[14:15], v[78:79]
	v_cvt_pk_bf16_f32 v100, v88, v89
	v_cvt_pk_bf16_f32 v101, v90, v91
	v_cvt_pk_bf16_f32 v102, v92, v93
	v_cvt_pk_bf16_f32 v103, v94, v95
	v_cvt_pk_bf16_f32 v104, v96, v97
	v_cvt_pk_bf16_f32 v105, v98, v99
	global_store_dwordx2 v2, v[100:101], s[6:7]
	global_store_dwordx2 v2, v[102:103], s[8:9]
	global_store_dwordx2 v2, v[104:105], s[10:11]
	s_add_u32 s6, s6, 0x1000
	s_addc_u32 s7, s7, 0
	s_add_u32 s8, s8, 0x1000
	s_addc_u32 s9, s9, 0
	s_add_u32 s10, s10, 0x1000
	s_addc_u32 s11, s11, 0
	s_waitcnt vmcnt(45)
	v_sub_f32_e32 v84, v76, v80
	v_sub_f32_e32 v85, v77, v81
	v_sub_f32_e32 v86, v78, v82
	v_sub_f32_e32 v87, v79, v83
	v_pk_fma_f32 v[88:89], v[84:85], v[4:5], v[80:81]
	v_pk_fma_f32 v[90:91], v[86:87], v[6:7], v[82:83]
	v_pk_fma_f32 v[92:93], v[84:85], v[8:9], v[80:81]
	v_pk_fma_f32 v[94:95], v[86:87], v[10:11], v[82:83]
	v_pk_fma_f32 v[96:97], v[84:85], v[12:13], v[80:81]
	v_pk_fma_f32 v[98:99], v[86:87], v[14:15], v[82:83]
	v_cvt_pk_bf16_f32 v106, v88, v89
	v_cvt_pk_bf16_f32 v107, v90, v91
	v_cvt_pk_bf16_f32 v108, v92, v93
	v_cvt_pk_bf16_f32 v109, v94, v95
	v_cvt_pk_bf16_f32 v110, v96, v97
	v_cvt_pk_bf16_f32 v111, v98, v99
	global_store_dwordx2 v2, v[106:107], s[6:7]
	global_store_dwordx2 v2, v[108:109], s[8:9]
	global_store_dwordx2 v2, v[110:111], s[10:11]
	s_add_u32 s6, s6, 0x1000
	s_addc_u32 s7, s7, 0
	s_add_u32 s8, s8, 0x1000
	s_addc_u32 s9, s9, 0
	s_add_u32 s10, s10, 0x1000
	s_addc_u32 s11, s11, 0
	v_mov_b32_e32 v16, v80
	v_mov_b32_e32 v17, v81
	v_mov_b32_e32 v18, v82
	v_mov_b32_e32 v19, v83
	s_branch .LBB0_70
.Lmix0_orig:
	s_mov_b64 s[4:5], s[0:1]
	s_mov_b64 s[6:7], s[0:1]
	s_mov_b64 s[14:15], s[0:1]
	v_mov_b32_e32 v1, v190
	s_mov_b32 s9, s2
	s_lshl_b32 s9, s9, 9
	v_readfirstlane_b32 s3, v1
	s_andn2_b32 s3, s3, 63
	s_add_i32 s9, s9, s3
	v_and_or_b32 v10, v1, 63, s9
	s_mov_b32 s3, 0x800000
	v_cmp_gt_i32_e32 vcc, s3, v10
	s_and_saveexec_b64 s[10:11], vcc
	s_cbranch_execz .LBB0_69
	s_load_dwordx2 s[12:13], s[6:7], 0x8
	s_load_dwordx2 s[16:17], s[4:5], 0x0
	s_load_dwordx2 s[20:21], s[14:15], 0xe0
	v_ashrrev_i32_e32 v11, 31, v10
	s_mov_b64 s[4:5], 0x8100000
	s_waitcnt lgkmcnt(0)
	s_add_u32 s14, s12, 0x4000
	s_addc_u32 s15, s13, 0
	v_lshl_add_u64 v[12:13], v[10:11], 4, s[16:17]
	s_add_u32 s16, s12, 0x6000
	s_addc_u32 s17, s13, 0
	s_ashr_i32 s9, s8, 31
	v_lshl_add_u64 v[2:3], v[10:11], 3, s[20:21]
	s_lshl_b64 s[18:19], s[8:9], 4
	v_lshl_add_u64 v[14:15], v[2:3], 0, s[4:5]
	s_lshl_b64 s[20:21], s[8:9], 3
	s_mov_b64 s[22:23], 0
	s_brev_b32 s3, 32
	s_mov_b32 s9, 0x7fffff
	s_branch .LBB0_67
